# P9 FF2+LN2 phase spread over all 256 workgroups as 192-row tiles (was 192 WGs x 256 rows); dead row groups skip MFMA
# speedup vs baseline: 1.0113x; 1.0113x over previous
.LBB0_640:
	s_or_b64 exec, exec, s[6:7]
	v_readlane_b32 s0, v242, 38
	v_readlane_b32 s1, v242, 39
	s_waitcnt lgkmcnt(0)
	s_barrier
	s_and_b64 vcc, exec, s[0:1]
	v_readfirstlane_b32 s34, v0
	v_lshlrev_b32_e32 v1, 4, v0
	v_add_u32_e32 v2, 0x2000, v1
	v_ashrrev_i32_e32 v3, 31, v2
	v_lshrrev_b32_e32 v3, 22, v3
	v_add_u32_e32 v3, v2, v3
	v_ashrrev_i32_e32 v10, 10, v3
	v_mul_i32_i24_e32 v3, 0x400, v10
	v_sub_u32_e32 v2, v2, v3
	v_lshrrev_b32_e32 v3, 4, v2
	v_bitop3_b32 v2, v3, v2, 32 bitop3:0x6c
	v_ashrrev_i32_e32 v3, 31, v2
	v_lshrrev_b32_e32 v3, 26, v3
	v_add_u32_e32 v3, v2, v3
	v_lshlrev_b32_e32 v4, 3, v10
	v_ashrrev_i32_e32 v11, 6, v3
	v_and_b32_e32 v4, -16, v4
	v_add_u32_e32 v4, v11, v4
	v_and_b32_e32 v5, 3, v11
	s_mov_b32 s0, 0x7ffe0
	v_lshrrev_b32_e32 v6, 2, v4
	v_lshlrev_b32_e32 v7, 1, v4
	v_and_b32_e32 v3, 0xc0, v3
	v_and_or_b32 v5, v4, s0, v5
	v_and_b32_e32 v6, 4, v6
	v_and_b32_e32 v7, 24, v7
	v_sub_u32_e32 v2, v2, v3
	v_mov_b32_e32 v3, 1
	v_or3_b32 v5, v5, v6, v7
	v_lshlrev_b32_e32 v6, 5, v10
	v_ashrrev_i16_sdwa v2, v3, sext(v2) dst_sel:DWORD dst_unused:UNUSED_PAD src0_sel:DWORD src1_sel:BYTE_0
	v_and_b32_e32 v6, 32, v6
	v_bfe_i32 v12, v2, 0, 16
	v_add_lshl_u32 v2, v6, v12, 1
	v_lshl_add_u32 v122, v5, 13, v2
	v_lshl_add_u32 v124, v4, 13, v2
	v_add_u32_e32 v124, 0xfffe0000, v124
	v_bfe_i32 v2, v0, 27, 1
	v_lshrrev_b32_e32 v2, 22, v2
	v_add_u32_e32 v2, v1, v2
	v_and_b32_e32 v2, 0xfffffc00, v2
	v_sub_u32_e32 v1, v1, v2
	v_lshrrev_b32_e32 v2, 4, v1
	v_ashrrev_i32_e32 v4, 31, v0
	v_bitop3_b32 v1, v2, v1, 32 bitop3:0x6c
	v_lshrrev_b32_e32 v4, 26, v4
	v_ashrrev_i32_e32 v2, 31, v1
	v_add_u32_e32 v4, v0, v4
	v_lshrrev_b32_e32 v2, 26, v2
	v_ashrrev_i32_e32 v14, 6, v4
	v_add_u32_e32 v2, v1, v2
	v_lshlrev_b32_e32 v4, 3, v14
	v_ashrrev_i32_e32 v13, 6, v2
	v_and_b32_e32 v4, -16, v4
	v_add_u32_e32 v4, v13, v4
	v_and_b32_e32 v5, 3, v13
	s_ashr_i32 s36, s38, 31
	v_and_or_b32 v5, v4, s0, v5
	s_lshr_b32 s0, s36, 29
	s_add_i32 s0, s38, s0
	s_ashr_i32 s3, s34, 6
	s_ashr_i32 s1, s0, 3
	s_and_b32 s0, s0, -8
	s_ashr_i32 s11, s34, 8
	s_lshl_b32 s35, s3, 10
	s_sub_i32 s0, s38, s0
	s_cmp_lt_i32 s0, 0
	s_cselect_b32 s4, 25, 24
	s_mul_i32 s0, s0, s4
	s_add_i32 s0, s0, s1
	s_mul_hi_i32 s1, s0, 0x2aaaaaab
	s_lshr_b32 s4, s1, 31
	s_ashr_i32 s1, s1, 2
	s_add_i32 s1, s1, s4
	s_mul_i32 s4, s1, 6
	s_mul_i32 s1, s1, 24
	s_sub_i32 s1, s0, s1
	s_mul_i32 s0, s1, 43
	s_bfe_u32 s5, s0, 0x1000f
	s_bfe_u32 s0, s0, 0x80008
	s_add_i32 s0, s0, s5
	s_mul_i32 s5, s0, 6
	s_sub_i32 s1, s1, s5
	s_sext_i32_i8 s1, s1
	v_lshrrev_b32_e32 v6, 2, v4
	v_lshlrev_b32_e32 v7, 1, v4
	v_and_b32_e32 v2, 0xc0, v2
	s_add_i32 s6, s4, s1
	v_and_b32_e32 v6, 4, v6
	v_and_b32_e32 v7, 24, v7
	v_sub_u32_e32 v1, v1, v2
	s_lshr_b32 s1, s38, 3
	s_and_b32 s0, s1, 3
	s_lshr_b32 s1, s1, 2
	s_and_b32 s6, s38, 7
	s_lshl_b32 s6, s6, 3
	s_add_i32 s6, s6, s1
	s_ashr_i32 s7, s6, 31
	s_bfe_i64 s[14:15], s[0:1], 0x80000
	v_or3_b32 v5, v5, v6, v7
	v_lshlrev_b32_e32 v6, 5, v14
	v_ashrrev_i16_sdwa v1, v3, sext(v1) dst_sel:DWORD dst_unused:UNUSED_PAD src0_sel:DWORD src1_sel:BYTE_0
	s_mul_i32 s4, s6, 0x180000
	s_mov_b32 s5, 0
	s_lshl_b64 s[14:15], s[14:15], 21
	v_and_b32_e32 v6, 32, v6
	v_bfe_i32 v15, v1, 0, 16
	s_add_u32 s26, s86, s14
	v_add_lshl_u32 v1, v6, v15, 1
	s_addc_u32 s27, s87, s15
	s_add_i32 s37, s35, 0
	v_lshl_add_u32 v134, v5, 13, v1
	s_add_i32 m0, s37, 0x10000
	v_lshl_add_u32 v136, v4, 13, v1
	global_load_lds_dwordx4 v134, s[26:27]
	s_add_i32 m0, s37, 0x12000
	s_add_u32 s14, s26, 0x100000
	global_load_lds_dwordx4 v122, s[26:27]
	s_addc_u32 s15, s27, 0
	s_add_i32 m0, s37, 0x14000
	v_mov_b32_e32 v135, 0
	global_load_lds_dwordx4 v134, s[14:15]
	s_add_i32 m0, s37, 0x16000
	v_mov_b32_e32 v123, v135
	global_load_lds_dwordx4 v122, s[14:15]
	s_add_u32 s14, s68, s4
	s_addc_u32 s15, s69, s5
	s_add_i32 s41, s37, 0x2000
	s_mov_b32 m0, s37
	s_add_u32 s4, s14, 0xc0000
	global_load_lds_dwordx4 v136, s[14:15]
	s_mov_b32 m0, s41
	s_addc_u32 s5, s15, 0
	s_add_i32 s42, s37, 0x4000
	global_load_lds_dwordx4 v124, s[14:15]
	s_mov_b32 m0, s42
	s_add_i32 s43, s37, 0x6000
	global_load_lds_dwordx4 v136, s[4:5]
	s_mov_b32 m0, s43
	v_mov_b32_e32 v137, v135
	global_load_lds_dwordx4 v124, s[4:5]
	v_mov_b32_e32 v125, v135
	s_mov_b32 s44, 0
	v_lshl_add_u64 v[8:9], s[26:27], 0, v[134:135]
	v_lshl_add_u64 v[6:7], s[26:27], 0, v[122:123]
	v_lshl_add_u64 v[4:5], s[14:15], 0, v[136:137]
	s_cmp_lg_u32 s11, 1
	v_lshl_add_u64 v[2:3], s[14:15], 0, v[124:125]
	s_cbranch_scc1 .LBB0_643
	s_barrier
.LBB0_643:
	v_and_b32_e32 v1, 15, v0
	v_and_b32_e32 v16, 48, v0
	v_lshlrev_b32_e32 v17, 2, v0
	s_mov_b64 s[16:17], 0x80
	s_sext_i32_i8 s10, s0
	s_and_b32 s7, s3, 3
	s_lshl_b32 s0, s11, 13
	v_lshl_or_b32 v16, v1, 6, v16
	v_and_b32_e32 v17, 32, v17
	s_add_i32 m0, s37, 0x18000
	v_lshl_add_u64 v[8:9], v[8:9], 0, s[16:17]
	s_lshl_b32 s40, s11, 6
	v_bitop3_b32 v18, v16, s0, v17 bitop3:0xde
	s_lshl_b32 s0, s7, 12
	s_waitcnt vmcnt(2)
	s_barrier
	global_load_lds_dwordx4 v[8:9], off
	v_lshl_add_u64 v[6:7], v[6:7], 0, s[16:17]
	s_add_i32 m0, s37, 0x1a000
	s_add_i32 s45, s37, 0x8000
	s_add_i32 s56, s37, 0xa000
	global_load_lds_dwordx4 v[6:7], off
	v_lshl_add_u64 v[4:5], v[4:5], 0, s[16:17]
	s_mov_b32 m0, s45
	s_add_u32 s4, s26, 0x100080
	global_load_lds_dwordx4 v[4:5], off
	v_lshl_add_u64 v[2:3], v[2:3], 0, s[16:17]
	s_mov_b32 m0, s56
	s_addc_u32 s5, s27, 0
	global_load_lds_dwordx4 v[2:3], off
	s_add_i32 m0, s37, 0x1c000
	v_lshl_add_u64 v[2:3], s[4:5], 0, v[134:135]
	global_load_lds_dwordx4 v[2:3], off
	v_lshl_add_u64 v[2:3], s[4:5], 0, v[122:123]
	s_add_i32 m0, s37, 0x1e000
	v_bitop3_b32 v150, v16, s0, v17 bitop3:0xde
	global_load_lds_dwordx4 v[2:3], off
	v_lshlrev_b32_e32 v2, 16, v14
	v_and_b32_e32 v2, 0xfffe0000, v2
	v_lshl_add_u32 v2, v13, 13, v2
	v_and_b32_e32 v3, 1, v14
	v_lshl_or_b32 v2, v3, 6, v2
	s_mov_b64 s[0:1], 0xc0080
	v_lshl_add_u32 v2, v15, 1, v2
	v_mov_b32_e32 v3, v135
	v_lshl_add_u64 v[138:139], v[2:3], 0, s[0:1]
	v_lshlrev_b32_e32 v2, 16, v10
	v_and_b32_e32 v2, 0xfffe0000, v2
	v_lshl_add_u32 v2, v11, 13, v2
	v_and_b32_e32 v3, 1, v10
	s_waitcnt vmcnt(6)
	v_lshl_or_b32 v2, v3, 6, v2
	v_lshl_add_u32 v2, v12, 1, v2
	v_mov_b32_e32 v3, v135
	v_or_b32_e32 v172, s40, v1
	v_add_u32_e32 v2, 0xfffe0000, v2
	v_lshl_add_u64 v[140:141], v[2:3], 0, s[0:1]
	v_mov_b64_e32 v[142:143], 0xc0
	v_mov_b64_e32 v[144:145], 0xbf
	s_add_i32 s57, 0, 0x10000
	s_add_i32 s58, 0, 0x14000
	v_add_u32_e32 v151, 0, v18
	v_mov_b32_e32 v2, v135
	v_mov_b32_e32 v4, v135
	v_mov_b32_e32 v5, v135
	v_mov_b32_e32 v6, v135
	v_mov_b32_e32 v7, v135
	v_mov_b32_e32 v8, v135
	v_mov_b32_e32 v9, v135
	v_mov_b32_e32 v14, v135
	v_mov_b32_e32 v15, v135
	v_mov_b32_e32 v16, v135
	v_mov_b32_e32 v17, v135
	v_mov_b32_e32 v22, v135
	v_mov_b32_e32 v23, v135
	v_mov_b32_e32 v24, v135
	v_mov_b32_e32 v25, v135
	v_mov_b32_e32 v30, v135
	v_mov_b32_e32 v31, v135
	v_mov_b32_e32 v32, v135
	v_mov_b32_e32 v33, v135
	v_mov_b32_e32 v38, v135
	v_mov_b32_e32 v39, v135
	v_mov_b32_e32 v40, v135
	v_mov_b32_e32 v41, v135
	v_mov_b32_e32 v46, v135
	v_mov_b32_e32 v47, v135
	v_mov_b32_e32 v48, v135
	v_mov_b32_e32 v49, v135
	v_mov_b32_e32 v54, v135
	v_mov_b32_e32 v55, v135
	v_mov_b32_e32 v56, v135
	v_mov_b32_e32 v57, v135
	v_mov_b32_e32 v10, v135
	v_mov_b32_e32 v11, v135
	v_mov_b32_e32 v12, v135
	v_mov_b32_e32 v13, v135
	v_mov_b32_e32 v18, v135
	v_mov_b32_e32 v19, v135
	v_mov_b32_e32 v20, v135
	v_mov_b32_e32 v21, v135
	v_mov_b32_e32 v26, v135
	v_mov_b32_e32 v27, v135
	v_mov_b32_e32 v28, v135
	v_mov_b32_e32 v29, v135
	v_mov_b32_e32 v34, v135
	v_mov_b32_e32 v35, v135
	v_mov_b32_e32 v36, v135
	v_mov_b32_e32 v37, v135
	v_mov_b32_e32 v42, v135
	v_mov_b32_e32 v43, v135
	v_mov_b32_e32 v44, v135
	v_mov_b32_e32 v45, v135
	v_mov_b32_e32 v50, v135
	v_mov_b32_e32 v51, v135
	v_mov_b32_e32 v52, v135
	v_mov_b32_e32 v53, v135
	v_mov_b32_e32 v58, v135
	v_mov_b32_e32 v59, v135
	v_mov_b32_e32 v60, v135
	v_mov_b32_e32 v61, v135
	v_mov_b32_e32 v62, v135
	v_mov_b32_e32 v63, v135
	v_mov_b32_e32 v64, v135
	v_mov_b32_e32 v65, v135
	v_mov_b32_e32 v66, v135
	v_mov_b32_e32 v67, v135
	v_mov_b32_e32 v68, v135
	v_mov_b32_e32 v69, v135
	v_mov_b32_e32 v70, v135
	v_mov_b32_e32 v71, v135
	v_mov_b32_e32 v72, v135
	v_mov_b32_e32 v73, v135
	v_mov_b32_e32 v94, v135
	v_mov_b32_e32 v95, v135
	v_mov_b32_e32 v96, v135
	v_mov_b32_e32 v97, v135
	v_mov_b32_e32 v110, v135
	v_mov_b32_e32 v111, v135
	v_mov_b32_e32 v112, v135
	v_mov_b32_e32 v113, v135
	v_mov_b32_e32 v90, v135
	v_mov_b32_e32 v91, v135
	v_mov_b32_e32 v92, v135
	v_mov_b32_e32 v93, v135
	v_mov_b32_e32 v86, v135
	v_mov_b32_e32 v87, v135
	v_mov_b32_e32 v88, v135
	v_mov_b32_e32 v89, v135
	v_mov_b32_e32 v82, v135
	v_mov_b32_e32 v83, v135
	v_mov_b32_e32 v84, v135
	v_mov_b32_e32 v85, v135
	v_mov_b32_e32 v98, v135
	v_mov_b32_e32 v99, v135
	v_mov_b32_e32 v100, v135
	v_mov_b32_e32 v101, v135
	v_mov_b32_e32 v74, v135
	v_mov_b32_e32 v75, v135
	v_mov_b32_e32 v76, v135
	v_mov_b32_e32 v77, v135
	v_mov_b32_e32 v102, v135
	v_mov_b32_e32 v103, v135
	v_mov_b32_e32 v104, v135
	v_mov_b32_e32 v105, v135
	v_mov_b32_e32 v118, v135
	v_mov_b32_e32 v119, v135
	v_mov_b32_e32 v120, v135
	v_mov_b32_e32 v121, v135
	v_mov_b32_e32 v126, v135
	v_mov_b32_e32 v127, v135
	v_mov_b32_e32 v128, v135
	v_mov_b32_e32 v129, v135
	v_mov_b32_e32 v78, v135
	v_mov_b32_e32 v79, v135
	v_mov_b32_e32 v80, v135
	v_mov_b32_e32 v81, v135
	v_mov_b32_e32 v130, v135
	v_mov_b32_e32 v131, v135
	v_mov_b32_e32 v132, v135
	v_mov_b32_e32 v133, v135
	v_mov_b32_e32 v106, v135
	v_mov_b32_e32 v107, v135
	v_mov_b32_e32 v108, v135
	v_mov_b32_e32 v109, v135
	v_mov_b32_e32 v114, v135
	v_mov_b32_e32 v115, v135
	v_mov_b32_e32 v116, v135
	v_mov_b32_e32 v117, v135
	s_barrier
	s_branch .LBB0_646

.LBB0_649:
	v_add_u32_e32 v164, s57, v150
	v_add_u32_e32 v173, s58, v150
	s_add_u32 s28, s14, s26
	ds_read_b128 v[152:155], v164
	ds_read_b128 v[156:159], v164 offset:1024
	ds_read_b128 v[160:163], v164 offset:2048
	ds_read_b128 v[164:167], v164 offset:3072
	ds_read_b128 v[168:171], v173
	ds_read_b128 v[174:177], v173 offset:1024
	ds_read_b128 v[178:181], v173 offset:2048
	ds_read_b128 v[182:185], v173 offset:3072
	s_addc_u32 s29, s15, s27
	s_add_u32 s28, s28, 0x100
	s_addc_u32 s29, s29, 0
	s_add_u32 s65, s60, s26
	s_addc_u32 s66, s61, s27
	s_cmpk_eq_i32 s26, 0x1f00
	s_cselect_b32 s31, s21, s29
	s_cselect_b32 s30, s62, s28
	s_cselect_b32 s29, s19, s66
	s_cselect_b32 s28, s63, s65
	v_lshl_add_u64 v[218:219], v[146:147], 0, s[26:27]
	s_add_i32 m0, s37, 0xc000
	ds_read_b128 v[186:189], v151
	ds_read_b128 v[190:193], v151 offset:1024
	ds_read_b128 v[194:197], v151 offset:2048
	ds_read_b128 v[198:201], v151 offset:3072
	ds_read_b128 v[202:205], v151 offset:4096
	ds_read_b128 v[206:209], v151 offset:5120
	global_load_lds_dwordx4 v[218:219], off
	v_lshl_add_u64 v[218:219], v[148:149], 0, s[26:27]
	s_add_i32 m0, s37, 0xe000
	s_nop 0
	global_load_lds_dwordx4 v[218:219], off
	s_waitcnt vmcnt(8)
	s_waitcnt lgkmcnt(0)
	s_barrier
	s_setprio 1
	s_waitcnt lgkmcnt(0)
	v_mfma_f32_16x16x32_bf16 v[114:117], v[152:155], v[186:189], v[114:117]
	v_mfma_f32_16x16x32_bf16 v[106:109], v[160:163], v[186:189], v[106:109]
	v_mfma_f32_16x16x32_bf16 v[130:133], v[152:155], v[194:197], v[130:133]
	v_mfma_f32_16x16x32_bf16 v[78:81], v[160:163], v[194:197], v[78:81]
	v_mfma_f32_16x16x32_bf16 v[126:129], v[152:155], v[202:205], v[126:129]
	v_mfma_f32_16x16x32_bf16 v[118:121], v[160:163], v[202:205], v[118:121]
	v_mfma_f32_16x16x32_bf16 v[114:117], v[156:159], v[190:193], v[114:117]
	v_mfma_f32_16x16x32_bf16 v[106:109], v[164:167], v[190:193], v[106:109]
	v_mfma_f32_16x16x32_bf16 v[130:133], v[156:159], v[198:201], v[130:133]
	v_mfma_f32_16x16x32_bf16 v[78:81], v[164:167], v[198:201], v[78:81]
	v_mfma_f32_16x16x32_bf16 v[126:129], v[156:159], v[206:209], v[126:129]
	v_mfma_f32_16x16x32_bf16 v[118:121], v[164:167], v[206:209], v[118:121]
	s_setprio 0
	s_setprio 1
	v_mfma_f32_16x16x32_bf16 v[98:101], v[168:171], v[186:189], v[98:101]
	v_mfma_f32_16x16x32_bf16 v[82:85], v[178:181], v[186:189], v[82:85]
	v_mfma_f32_16x16x32_bf16 v[86:89], v[168:171], v[194:197], v[86:89]
	v_mfma_f32_16x16x32_bf16 v[90:93], v[178:181], v[194:197], v[90:93]
	v_mfma_f32_16x16x32_bf16 v[110:113], v[168:171], v[202:205], v[110:113]
	v_mfma_f32_16x16x32_bf16 v[94:97], v[178:181], v[202:205], v[94:97]
	v_mfma_f32_16x16x32_bf16 v[98:101], v[174:177], v[190:193], v[98:101]
	v_mfma_f32_16x16x32_bf16 v[82:85], v[182:185], v[190:193], v[82:85]
	v_mfma_f32_16x16x32_bf16 v[86:89], v[174:177], v[198:201], v[86:89]
	v_mfma_f32_16x16x32_bf16 v[90:93], v[182:185], v[198:201], v[90:93]
	v_mfma_f32_16x16x32_bf16 v[110:113], v[174:177], v[206:209], v[110:113]
	v_mfma_f32_16x16x32_bf16 v[94:97], v[182:185], v[206:209], v[94:97]
	s_setprio 0
	s_barrier
	s_add_i32 s65, s57, s35
	v_lshl_add_u64 v[218:219], s[28:29], 0, v[134:135]
	s_mov_b32 m0, s65
	ds_read_b128 v[186:189], v151 offset:16384
	ds_read_b128 v[190:193], v151 offset:17408
	ds_read_b128 v[194:197], v151 offset:18432
	ds_read_b128 v[198:201], v151 offset:19456
	ds_read_b128 v[202:205], v151 offset:20480
	ds_read_b128 v[206:209], v151 offset:21504
	global_load_lds_dwordx4 v[218:219], off
	s_add_i32 m0, s65, 0x2000
	s_add_u32 s66, s28, 0x100000
	v_lshl_add_u64 v[220:221], s[28:29], 0, v[122:123]
	s_addc_u32 s67, s29, 0
	s_add_i32 s65, s58, s35
	global_load_lds_dwordx4 v[220:221], off
	v_lshl_add_u64 v[222:223], s[66:67], 0, v[134:135]
	s_mov_b32 m0, s65
	v_lshl_add_u64 v[224:225], s[30:31], 0, v[124:125]
	global_load_lds_dwordx4 v[222:223], off
	v_lshl_add_u64 v[222:223], s[66:67], 0, v[122:123]
	s_add_i32 m0, s65, 0x2000
	s_nop 0
	global_load_lds_dwordx4 v[222:223], off
	v_lshl_add_u64 v[222:223], s[30:31], 0, v[136:137]
	s_mov_b32 m0, s37
	s_nop 0
	global_load_lds_dwordx4 v[222:223], off
	s_mov_b32 m0, s41
	s_nop 0
	global_load_lds_dwordx4 v[224:225], off
	s_waitcnt vmcnt(8)
	s_waitcnt lgkmcnt(0)
	s_barrier
	s_setprio 1
	s_waitcnt lgkmcnt(0)
	v_mfma_f32_16x16x32_bf16 v[62:65], v[152:155], v[186:189], v[62:65]
	v_mfma_f32_16x16x32_bf16 v[58:61], v[160:163], v[186:189], v[58:61]
	v_mfma_f32_16x16x32_bf16 v[50:53], v[152:155], v[194:197], v[50:53]
	v_mfma_f32_16x16x32_bf16 v[42:45], v[160:163], v[194:197], v[42:45]
	v_mfma_f32_16x16x32_bf16 v[34:37], v[152:155], v[202:205], v[34:37]
	v_mfma_f32_16x16x32_bf16 v[26:29], v[160:163], v[202:205], v[26:29]
	v_mfma_f32_16x16x32_bf16 v[62:65], v[156:159], v[190:193], v[62:65]
	v_mfma_f32_16x16x32_bf16 v[58:61], v[164:167], v[190:193], v[58:61]
	v_mfma_f32_16x16x32_bf16 v[50:53], v[156:159], v[198:201], v[50:53]
	v_mfma_f32_16x16x32_bf16 v[42:45], v[164:167], v[198:201], v[42:45]
	v_mfma_f32_16x16x32_bf16 v[34:37], v[156:159], v[206:209], v[34:37]
	v_mfma_f32_16x16x32_bf16 v[26:29], v[164:167], v[206:209], v[26:29]
	s_setprio 0
	s_setprio 1
	v_mfma_f32_16x16x32_bf16 v[54:57], v[168:171], v[186:189], v[54:57]
	v_mfma_f32_16x16x32_bf16 v[46:49], v[178:181], v[186:189], v[46:49]
	v_mfma_f32_16x16x32_bf16 v[38:41], v[168:171], v[194:197], v[38:41]
	v_mfma_f32_16x16x32_bf16 v[30:33], v[178:181], v[194:197], v[30:33]
	v_mfma_f32_16x16x32_bf16 v[22:25], v[168:171], v[202:205], v[22:25]
	v_mfma_f32_16x16x32_bf16 v[14:17], v[178:181], v[202:205], v[14:17]
	v_mfma_f32_16x16x32_bf16 v[54:57], v[174:177], v[190:193], v[54:57]
	v_mfma_f32_16x16x32_bf16 v[46:49], v[182:185], v[190:193], v[46:49]
	v_mfma_f32_16x16x32_bf16 v[38:41], v[174:177], v[198:201], v[38:41]
	v_mfma_f32_16x16x32_bf16 v[30:33], v[182:185], v[198:201], v[30:33]
	v_mfma_f32_16x16x32_bf16 v[22:25], v[174:177], v[206:209], v[22:25]
	v_mfma_f32_16x16x32_bf16 v[14:17], v[182:185], v[206:209], v[14:17]
	s_setprio 0
	s_barrier
	s_add_i32 s65, 0, 0x18000
	s_add_i32 s66, 0, 0x1c000
	v_add_u32_e32 v164, s65, v150
	v_add_u32_e32 v173, s66, v150
	ds_read_b128 v[152:155], v164
	ds_read_b128 v[156:159], v164 offset:1024
	ds_read_b128 v[160:163], v164 offset:2048
	ds_read_b128 v[164:167], v164 offset:3072
	ds_read_b128 v[168:171], v173
	ds_read_b128 v[174:177], v173 offset:1024
	ds_read_b128 v[178:181], v173 offset:2048
	ds_read_b128 v[182:185], v173 offset:3072
	s_add_u32 s30, s30, 0xc0000
	s_addc_u32 s31, s31, 0
	s_mov_b32 m0, s42
	v_lshl_add_u64 v[226:227], s[30:31], 0, v[136:137]
	ds_read_b128 v[186:189], v151 offset:32768
	ds_read_b128 v[190:193], v151 offset:33792
	ds_read_b128 v[194:197], v151 offset:34816
	ds_read_b128 v[198:201], v151 offset:35840
	ds_read_b128 v[202:205], v151 offset:36864
	ds_read_b128 v[206:209], v151 offset:37888
	global_load_lds_dwordx4 v[226:227], off
	v_lshl_add_u64 v[226:227], s[30:31], 0, v[124:125]
	s_mov_b32 m0, s43
	s_nop 0
	global_load_lds_dwordx4 v[226:227], off
	s_waitcnt vmcnt(8)
	s_waitcnt lgkmcnt(0)
	s_barrier
	s_setprio 1
	s_waitcnt lgkmcnt(0)
	v_mfma_f32_16x16x32_bf16 v[114:117], v[152:155], v[186:189], v[114:117]
	v_mfma_f32_16x16x32_bf16 v[106:109], v[160:163], v[186:189], v[106:109]
	v_mfma_f32_16x16x32_bf16 v[130:133], v[152:155], v[194:197], v[130:133]
	v_mfma_f32_16x16x32_bf16 v[78:81], v[160:163], v[194:197], v[78:81]
	v_mfma_f32_16x16x32_bf16 v[126:129], v[152:155], v[202:205], v[126:129]
	v_mfma_f32_16x16x32_bf16 v[118:121], v[160:163], v[202:205], v[118:121]
	v_mfma_f32_16x16x32_bf16 v[114:117], v[156:159], v[190:193], v[114:117]
	v_mfma_f32_16x16x32_bf16 v[106:109], v[164:167], v[190:193], v[106:109]
	v_mfma_f32_16x16x32_bf16 v[130:133], v[156:159], v[198:201], v[130:133]
	v_mfma_f32_16x16x32_bf16 v[78:81], v[164:167], v[198:201], v[78:81]
	v_mfma_f32_16x16x32_bf16 v[126:129], v[156:159], v[206:209], v[126:129]
	v_mfma_f32_16x16x32_bf16 v[118:121], v[164:167], v[206:209], v[118:121]
	s_setprio 0
	s_setprio 1
	v_mfma_f32_16x16x32_bf16 v[98:101], v[168:171], v[186:189], v[98:101]
	v_mfma_f32_16x16x32_bf16 v[82:85], v[178:181], v[186:189], v[82:85]
	v_mfma_f32_16x16x32_bf16 v[86:89], v[168:171], v[194:197], v[86:89]
	v_mfma_f32_16x16x32_bf16 v[90:93], v[178:181], v[194:197], v[90:93]
	v_mfma_f32_16x16x32_bf16 v[110:113], v[168:171], v[202:205], v[110:113]
	v_mfma_f32_16x16x32_bf16 v[94:97], v[178:181], v[202:205], v[94:97]
	v_mfma_f32_16x16x32_bf16 v[98:101], v[174:177], v[190:193], v[98:101]
	v_mfma_f32_16x16x32_bf16 v[82:85], v[182:185], v[190:193], v[82:85]
	v_mfma_f32_16x16x32_bf16 v[86:89], v[174:177], v[198:201], v[86:89]
	v_mfma_f32_16x16x32_bf16 v[90:93], v[182:185], v[198:201], v[90:93]
	v_mfma_f32_16x16x32_bf16 v[110:113], v[174:177], v[206:209], v[110:113]
	v_mfma_f32_16x16x32_bf16 v[94:97], v[182:185], v[206:209], v[94:97]
	s_setprio 0
	s_barrier
	s_add_i32 s30, s65, s35
	v_lshl_add_u64 v[218:219], v[218:219], 0, s[16:17]
	s_mov_b32 m0, s30
	ds_read_b128 v[186:189], v151 offset:49152
	ds_read_b128 v[190:193], v151 offset:50176
	ds_read_b128 v[194:197], v151 offset:51200
	ds_read_b128 v[198:201], v151 offset:52224
	ds_read_b128 v[202:205], v151 offset:53248
	ds_read_b128 v[206:209], v151 offset:54272
	global_load_lds_dwordx4 v[218:219], off
	s_add_i32 m0, s30, 0x2000
	s_add_u32 s28, s28, 0x100080
	v_lshl_add_u64 v[218:219], v[220:221], 0, s[16:17]
	s_addc_u32 s29, s29, 0
	s_add_i32 s30, s66, s35
	global_load_lds_dwordx4 v[218:219], off
	v_lshl_add_u64 v[218:219], s[28:29], 0, v[134:135]
	s_mov_b32 m0, s30
	s_nop 0
	global_load_lds_dwordx4 v[218:219], off
	v_lshl_add_u64 v[218:219], s[28:29], 0, v[122:123]
	s_add_i32 m0, s30, 0x2000
	s_nop 0
	global_load_lds_dwordx4 v[218:219], off
	v_lshl_add_u64 v[218:219], v[222:223], 0, s[16:17]
	s_mov_b32 m0, s45
	s_nop 0
	global_load_lds_dwordx4 v[218:219], off
	v_lshl_add_u64 v[218:219], v[224:225], 0, s[16:17]
	s_mov_b32 m0, s56
	s_nop 0
	global_load_lds_dwordx4 v[218:219], off
	s_waitcnt vmcnt(8)
	s_waitcnt lgkmcnt(0)
	s_barrier
	s_setprio 1
	s_waitcnt lgkmcnt(0)
	v_mfma_f32_16x16x32_bf16 v[62:65], v[152:155], v[186:189], v[62:65]
	v_mfma_f32_16x16x32_bf16 v[58:61], v[160:163], v[186:189], v[58:61]
	v_mfma_f32_16x16x32_bf16 v[50:53], v[152:155], v[194:197], v[50:53]
	v_mfma_f32_16x16x32_bf16 v[42:45], v[160:163], v[194:197], v[42:45]
	v_mfma_f32_16x16x32_bf16 v[34:37], v[152:155], v[202:205], v[34:37]
	v_mfma_f32_16x16x32_bf16 v[26:29], v[160:163], v[202:205], v[26:29]
	v_mfma_f32_16x16x32_bf16 v[62:65], v[156:159], v[190:193], v[62:65]
	v_mfma_f32_16x16x32_bf16 v[58:61], v[164:167], v[190:193], v[58:61]
	v_mfma_f32_16x16x32_bf16 v[50:53], v[156:159], v[198:201], v[50:53]
	v_mfma_f32_16x16x32_bf16 v[42:45], v[164:167], v[198:201], v[42:45]
	v_mfma_f32_16x16x32_bf16 v[34:37], v[156:159], v[206:209], v[34:37]
	v_mfma_f32_16x16x32_bf16 v[26:29], v[164:167], v[206:209], v[26:29]
	s_setprio 0
	s_setprio 1
	v_mfma_f32_16x16x32_bf16 v[54:57], v[168:171], v[186:189], v[54:57]
	v_mfma_f32_16x16x32_bf16 v[46:49], v[178:181], v[186:189], v[46:49]
	v_mfma_f32_16x16x32_bf16 v[38:41], v[168:171], v[194:197], v[38:41]
	v_mfma_f32_16x16x32_bf16 v[30:33], v[178:181], v[194:197], v[30:33]
	v_mfma_f32_16x16x32_bf16 v[22:25], v[168:171], v[202:205], v[22:25]
	v_mfma_f32_16x16x32_bf16 v[14:17], v[178:181], v[202:205], v[14:17]
	v_mfma_f32_16x16x32_bf16 v[54:57], v[174:177], v[190:193], v[54:57]
	v_mfma_f32_16x16x32_bf16 v[46:49], v[182:185], v[190:193], v[46:49]
	v_mfma_f32_16x16x32_bf16 v[38:41], v[174:177], v[198:201], v[38:41]
	v_mfma_f32_16x16x32_bf16 v[30:33], v[182:185], v[198:201], v[30:33]
	v_mfma_f32_16x16x32_bf16 v[22:25], v[174:177], v[206:209], v[22:25]
	v_mfma_f32_16x16x32_bf16 v[14:17], v[182:185], v[206:209], v[14:17]
	s_setprio 0
	s_barrier
	s_add_i32 s64, s64, 2
	s_add_u32 s26, s26, 0x100
	s_addc_u32 s27, s27, 0
	s_cmp_gt_u32 s64, 61
	s_cbranch_scc0 .LBB0_649
	s_add_u32 s26, s60, 0xffffff00
	s_addc_u32 s27, s61, -1
	s_andn2_b64 vcc, exec, s[4:5]
	s_cbranch_vccnz .LBB0_644
	v_mov_b32_e32 v2, 0
	s_mov_b32 s10, s18
	s_mov_b32 s6, s20
	s_mov_b64 s[14:15], s[24:25]
	s_mov_b32 s44, s59
	v_mov_b32_e32 v3, v2
	v_mov_b32_e32 v4, v2
	v_mov_b32_e32 v5, v2
	v_mov_b32_e32 v6, v2
	v_mov_b32_e32 v7, v2
	v_mov_b32_e32 v8, v2
	v_mov_b32_e32 v9, v2
	v_mov_b32_e32 v14, v2
	v_mov_b32_e32 v15, v2
	v_mov_b32_e32 v16, v2
	v_mov_b32_e32 v17, v2
	v_mov_b32_e32 v22, v2
	v_mov_b32_e32 v23, v2
	v_mov_b32_e32 v24, v2
	v_mov_b32_e32 v25, v2
	v_mov_b32_e32 v30, v2
	v_mov_b32_e32 v31, v2
	v_mov_b32_e32 v32, v2
	v_mov_b32_e32 v33, v2
	v_mov_b32_e32 v38, v2
	v_mov_b32_e32 v39, v2
	v_mov_b32_e32 v40, v2
	v_mov_b32_e32 v41, v2
	v_mov_b32_e32 v46, v2
	v_mov_b32_e32 v47, v2
	v_mov_b32_e32 v48, v2
	v_mov_b32_e32 v49, v2
	v_mov_b32_e32 v54, v2
	v_mov_b32_e32 v55, v2
	v_mov_b32_e32 v56, v2
	v_mov_b32_e32 v57, v2
	v_mov_b32_e32 v10, v2
	v_mov_b32_e32 v11, v2
	v_mov_b32_e32 v12, v2
	v_mov_b32_e32 v13, v2
	v_mov_b32_e32 v18, v2
	v_mov_b32_e32 v19, v2
	v_mov_b32_e32 v20, v2
	v_mov_b32_e32 v21, v2
	v_mov_b32_e32 v26, v2
	v_mov_b32_e32 v27, v2
	v_mov_b32_e32 v28, v2
	v_mov_b32_e32 v29, v2
	v_mov_b32_e32 v34, v2
	v_mov_b32_e32 v35, v2
	v_mov_b32_e32 v36, v2
	v_mov_b32_e32 v37, v2
	v_mov_b32_e32 v42, v2
	v_mov_b32_e32 v43, v2
	v_mov_b32_e32 v44, v2
	v_mov_b32_e32 v45, v2
	v_mov_b32_e32 v50, v2
	v_mov_b32_e32 v51, v2
	v_mov_b32_e32 v52, v2
	v_mov_b32_e32 v53, v2
	v_mov_b32_e32 v58, v2
	v_mov_b32_e32 v59, v2
	v_mov_b32_e32 v60, v2
	v_mov_b32_e32 v61, v2
	v_mov_b32_e32 v62, v2
	v_mov_b32_e32 v63, v2
	v_mov_b32_e32 v64, v2
	v_mov_b32_e32 v65, v2
	v_mov_b32_e32 v66, v2
	v_mov_b32_e32 v67, v2
	v_mov_b32_e32 v68, v2
	v_mov_b32_e32 v69, v2
	v_mov_b32_e32 v70, v2
	v_mov_b32_e32 v71, v2
	v_mov_b32_e32 v72, v2
	v_mov_b32_e32 v73, v2
	v_mov_b32_e32 v94, v2
	v_mov_b32_e32 v95, v2
	v_mov_b32_e32 v96, v2
	v_mov_b32_e32 v97, v2
	v_mov_b32_e32 v110, v2
	v_mov_b32_e32 v111, v2
	v_mov_b32_e32 v112, v2
	v_mov_b32_e32 v113, v2
	v_mov_b32_e32 v90, v2
	v_mov_b32_e32 v91, v2
	v_mov_b32_e32 v92, v2
	v_mov_b32_e32 v93, v2
	v_mov_b32_e32 v86, v2
	v_mov_b32_e32 v87, v2
	v_mov_b32_e32 v88, v2
	v_mov_b32_e32 v89, v2
	v_mov_b32_e32 v82, v2
	v_mov_b32_e32 v83, v2
	v_mov_b32_e32 v84, v2
	v_mov_b32_e32 v85, v2
	v_mov_b32_e32 v98, v2
	v_mov_b32_e32 v99, v2
	v_mov_b32_e32 v100, v2
	v_mov_b32_e32 v101, v2
	v_mov_b32_e32 v74, v2
	v_mov_b32_e32 v75, v2
	v_mov_b32_e32 v76, v2
	v_mov_b32_e32 v77, v2
	v_mov_b32_e32 v102, v2
	v_mov_b32_e32 v103, v2
	v_mov_b32_e32 v104, v2
	v_mov_b32_e32 v105, v2
	v_mov_b32_e32 v118, v2
	v_mov_b32_e32 v119, v2
	v_mov_b32_e32 v120, v2
	v_mov_b32_e32 v121, v2
	v_mov_b32_e32 v126, v2
	v_mov_b32_e32 v127, v2
	v_mov_b32_e32 v128, v2
	v_mov_b32_e32 v129, v2
	v_mov_b32_e32 v78, v2
	v_mov_b32_e32 v79, v2
	v_mov_b32_e32 v80, v2
	v_mov_b32_e32 v81, v2
	v_mov_b32_e32 v130, v2
	v_mov_b32_e32 v131, v2
	v_mov_b32_e32 v132, v2
	v_mov_b32_e32 v133, v2
	v_mov_b32_e32 v106, v2
	v_mov_b32_e32 v107, v2
	v_mov_b32_e32 v108, v2
	v_mov_b32_e32 v109, v2
	v_mov_b32_e32 v114, v2
	v_mov_b32_e32 v115, v2
	v_mov_b32_e32 v116, v2
	v_mov_b32_e32 v117, v2
	s_andn2_b64 vcc, exec, s[0:1]
	s_cbranch_vccnz .LBB0_645

.LBB0_654:
	s_lshl_b32 s0, s7, 5
	s_lshl_b32 s1, s10, 8
	v_lshrrev_b32_e32 v122, 1, v0
	s_or_b32 s0, s1, s0
	v_and_or_b32 v122, v122, 24, s0
	s_mul_i32 s98, s6, 0xc0
	s_add_i32 s0, s98, 0xfffff000
	s_ashr_i32 s0, s0, 11
	s_add_i32 s0, s0, 1
	s_max_i32 s0, s0, 0
	s_mulk_i32 s0, 0x1800
	s_add_i32 s101, s98, 0xbf
	s_lshr_b32 s101, s101, 11
	s_lshl_b32 s101, s101, 11
	s_sub_i32 s101, s101, s98
	s_mov_b32 s100, 99
	s_cmp_lt_i32 s101, 1
	s_cbranch_scc1 .Lp9_nostraddle
	s_add_i32 s99, s98, s101
	s_cmp_lt_u32 s99, 0x1000
	s_cbranch_scc1 .Lp9_nostraddle
	s_cmp_eq_u32 s101, 64
	s_cselect_b32 s100, 4, 6
	s_cselect_b32 s99, 1, 4
	s_cmp_eq_u32 s40, 0
	s_cselect_b32 s100, s100, s99
.Lp9_nostraddle:
	s_lshr_b32 s99, s40, 2
	s_sub_i32 s99, s98, s99
	s_mov_b32 s1, 0
	s_lshl_b64 s[0:1], s[0:1], 2
	v_readlane_b32 s4, v242, 34
	v_readlane_b32 s5, v242, 35
	s_add_u32 s0, s4, s0
	s_addc_u32 s1, s5, s1
	s_lshl_b32 s18, s6, 8
	v_ashrrev_i32_e32 v123, 31, v122
	s_add_i32 s2, s99, s40
	v_lshlrev_b64 v[166:167], 2, v[122:123]
	v_or_b32_e32 v168, s2, v1
	v_lshl_add_u64 v[124:125], s[46:47], 0, v[166:167]
	v_ashrrev_i32_e32 v169, 31, v168
	s_barrier
	global_load_dwordx4 v[146:149], v[124:125], off offset:16
	global_load_dwordx4 v[154:157], v[124:125], off
	global_load_dwordx4 v[134:137], v[124:125], off offset:528
	global_load_dwordx4 v[138:141], v[124:125], off offset:512
	v_lshlrev_b64 v[124:125], 11, v[168:169]
	v_lshl_add_u64 v[124:125], s[84:85], 0, v[124:125]
	v_lshlrev_b64 v[170:171], 1, v[122:123]
	v_lshl_add_u64 v[142:143], v[124:125], 0, v[170:171]
	global_load_dwordx4 v[122:125], v[142:143], off
	global_load_dwordx4 v[174:177], v[142:143], off offset:256
	v_lshl_add_u64 v[142:143], s[0:1], 0, v[166:167]
	s_movk_i32 s2, 0x5000
	v_add_u32_e32 v178, 16, v168
	s_mov_b64 s[0:1], 0x5000
	v_add_co_u32_e32 v144, vcc, s2, v142
	v_ashrrev_i32_e32 v179, 31, v178
	s_nop 0
	v_addc_co_u32_e32 v145, vcc, 0, v143, vcc
	v_add_co_u32_e32 v240, vcc, 0xb000, v142
	s_nop 1
	v_addc_co_u32_e32 v241, vcc, 0, v143, vcc
	v_lshl_add_u64 v[142:143], v[142:143], 0, s[0:1]
	v_lshlrev_b64 v[178:179], 11, v[178:179]
	global_load_dwordx4 v[162:165], v[144:145], off
	global_load_dwordx4 v[158:161], v[142:143], off offset:16
	global_load_dwordx4 v[150:153], v[142:143], off offset:512
	s_nop 0
	global_load_dwordx4 v[142:145], v[142:143], off offset:528
	v_lshl_add_u64 v[178:179], s[84:85], 0, v[178:179]
	v_lshl_add_u64 v[182:183], v[178:179], 0, v[170:171]
	global_load_dwordx4 v[178:181], v[182:183], off
	s_nop 0
	global_load_dwordx4 v[182:185], v[182:183], off offset:256
	v_add_u32_e32 v186, 32, v168
	v_ashrrev_i32_e32 v187, 31, v186
	s_mov_b32 s0, 0x3f9837f0
	v_lshlrev_b64 v[186:187], 11, v[186:187]
	v_lshl_add_u64 v[186:187], s[84:85], 0, v[186:187]
	s_waitcnt vmcnt(0)
	v_pk_add_f32 v[108:109], v[108:109], v[148:149]
	v_pk_add_f32 v[116:117], v[116:117], v[156:157]
	v_pk_add_f32 v[114:115], v[114:115], v[154:155]
	v_pk_add_f32 v[106:107], v[106:107], v[146:147]
	v_pk_add_f32 v[100:101], v[100:101], v[140:141]
	v_pk_add_f32 v[98:99], v[98:99], v[138:139]
	v_pk_add_f32 v[84:85], v[84:85], v[136:137]
	v_lshlrev_b32_e32 v188, 16, v122
	v_and_b32_e32 v189, 0xffff0000, v122
	v_lshlrev_b32_e32 v122, 16, v123
	v_and_b32_e32 v123, 0xffff0000, v123
	v_lshlrev_b32_e32 v190, 16, v124
	v_and_b32_e32 v191, 0xffff0000, v124
	v_lshlrev_b32_e32 v124, 16, v125
	v_and_b32_e32 v125, 0xffff0000, v125
	v_lshlrev_b32_e32 v192, 16, v174
	v_and_b32_e32 v193, 0xffff0000, v174
	v_lshlrev_b32_e32 v174, 16, v175
	v_and_b32_e32 v175, 0xffff0000, v175
	v_lshlrev_b32_e32 v194, 16, v176
	v_and_b32_e32 v195, 0xffff0000, v176
	v_lshlrev_b32_e32 v176, 16, v177
	v_and_b32_e32 v177, 0xffff0000, v177
	v_pk_add_f32 v[82:83], v[82:83], v[134:135]
	v_pk_mul_f32 v[196:197], v[122:123], s[0:1] op_sel_hi:[1,0]
	v_pk_mul_f32 v[122:123], v[188:189], s[0:1] op_sel_hi:[1,0]
	v_pk_mul_f32 v[188:189], v[190:191], s[0:1] op_sel_hi:[1,0]
	v_pk_mul_f32 v[190:191], v[124:125], s[0:1] op_sel_hi:[1,0]
	v_pk_mul_f32 v[192:193], v[192:193], s[0:1] op_sel_hi:[1,0]
	v_pk_mul_f32 v[174:175], v[174:175], s[0:1] op_sel_hi:[1,0]
	v_pk_mul_f32 v[194:195], v[194:195], s[0:1] op_sel_hi:[1,0]
	v_pk_mul_f32 v[176:177], v[176:177], s[0:1] op_sel_hi:[1,0]
	v_pk_fma_f32 v[122:123], v[162:163], v[114:115], v[122:123]
	v_pk_fma_f32 v[124:125], v[164:165], v[116:117], v[196:197]
	v_pk_fma_f32 v[116:117], v[160:161], v[108:109], v[190:191]
	v_pk_fma_f32 v[114:115], v[158:159], v[106:107], v[188:189]
	v_pk_fma_f32 v[108:109], v[152:153], v[100:101], v[174:175]
	v_pk_fma_f32 v[106:107], v[150:151], v[98:99], v[192:193]
	v_pk_fma_f32 v[100:101], v[144:145], v[84:85], v[176:177]
	v_pk_fma_f32 v[98:99], v[142:143], v[82:83], v[194:195]
	v_lshl_add_u64 v[82:83], v[186:187], 0, v[170:171]
	s_cmp_eq_u32 s100, 1
	s_cbranch_scc0 .Lp9_gate_1
	global_load_dwordx4 v[162:165], v[240:241], off
	global_load_dwordx4 v[158:161], v[240:241], off offset:16
	global_load_dwordx4 v[150:153], v[240:241], off offset:512
	global_load_dwordx4 v[142:145], v[240:241], off offset:528
	s_waitcnt vmcnt(0)
.Lp9_gate_1:
	global_load_dwordx4 v[174:177], v[82:83], off offset:256
	global_load_dwordx4 v[186:189], v[82:83], off
	v_lshlrev_b32_e32 v82, 16, v178
	v_and_b32_e32 v83, 0xffff0000, v178
	v_pk_mul_f32 v[82:83], v[82:83], s[0:1] op_sel_hi:[1,0]
	v_pk_add_f32 v[130:131], v[130:131], v[154:155]
	v_pk_add_f32 v[78:79], v[78:79], v[146:147]
	v_pk_fma_f32 v[82:83], v[162:163], v[130:131], v[82:83]
	v_lshlrev_b32_e32 v130, 16, v180
	v_and_b32_e32 v131, 0xffff0000, v180
	v_pk_mul_f32 v[130:131], v[130:131], s[0:1] op_sel_hi:[1,0]
	v_lshlrev_b32_e32 v84, 16, v179
	v_and_b32_e32 v85, 0xffff0000, v179
	v_pk_fma_f32 v[78:79], v[158:159], v[78:79], v[130:131]
	v_lshlrev_b32_e32 v130, 16, v182
	v_and_b32_e32 v131, 0xffff0000, v182
	v_pk_mul_f32 v[84:85], v[84:85], s[0:1] op_sel_hi:[1,0]
	v_pk_add_f32 v[132:133], v[132:133], v[156:157]
	v_pk_mul_f32 v[130:131], v[130:131], s[0:1] op_sel_hi:[1,0]
	v_pk_add_f32 v[86:87], v[86:87], v[138:139]
	v_pk_fma_f32 v[84:85], v[164:165], v[132:133], v[84:85]
	v_lshlrev_b32_e32 v132, 16, v181
	v_and_b32_e32 v133, 0xffff0000, v181
	v_pk_fma_f32 v[86:87], v[150:151], v[86:87], v[130:131]
	v_lshlrev_b32_e32 v130, 16, v184
	v_and_b32_e32 v131, 0xffff0000, v184
	v_pk_mul_f32 v[132:133], v[132:133], s[0:1] op_sel_hi:[1,0]
	v_pk_add_f32 v[80:81], v[80:81], v[148:149]
	v_pk_mul_f32 v[130:131], v[130:131], s[0:1] op_sel_hi:[1,0]
	v_pk_add_f32 v[90:91], v[90:91], v[134:135]
	v_pk_fma_f32 v[80:81], v[160:161], v[80:81], v[132:133]
	v_lshlrev_b32_e32 v132, 16, v183
	v_and_b32_e32 v133, 0xffff0000, v183
	v_pk_fma_f32 v[90:91], v[142:143], v[90:91], v[130:131]
	v_add_u32_e32 v130, 48, v168
	v_pk_mul_f32 v[132:133], v[132:133], s[0:1] op_sel_hi:[1,0]
	v_pk_add_f32 v[88:89], v[88:89], v[140:141]
	v_ashrrev_i32_e32 v131, 31, v130
	v_pk_fma_f32 v[88:89], v[152:153], v[88:89], v[132:133]
	v_lshlrev_b32_e32 v132, 16, v185
	v_and_b32_e32 v133, 0xffff0000, v185
	v_lshlrev_b64 v[130:131], 11, v[130:131]
	v_pk_mul_f32 v[132:133], v[132:133], s[0:1] op_sel_hi:[1,0]
	v_pk_add_f32 v[92:93], v[92:93], v[136:137]
	v_lshl_add_u64 v[130:131], s[84:85], 0, v[130:131]
	v_pk_fma_f32 v[92:93], v[144:145], v[92:93], v[132:133]
	v_lshl_add_u64 v[178:179], v[130:131], 0, v[170:171]
	global_load_dwordx4 v[130:133], v[178:179], off
	s_nop 0
	global_load_dwordx4 v[178:181], v[178:179], off offset:256
	v_pk_add_f32 v[112:113], v[112:113], v[140:141]
	v_pk_add_f32 v[118:119], v[118:119], v[146:147]
	v_pk_add_f32 v[96:97], v[96:97], v[136:137]
	v_pk_add_f32 v[104:105], v[104:105], v[156:157]
	v_pk_add_f32 v[128:129], v[128:129], v[156:157]
	v_pk_add_f32 v[126:127], v[126:127], v[154:155]
	v_pk_add_f32 v[120:121], v[120:121], v[148:149]
	v_pk_add_f32 v[110:111], v[110:111], v[138:139]
	v_pk_add_f32 v[94:95], v[94:95], v[134:135]
	v_pk_add_f32 v[74:75], v[74:75], v[146:147]
	v_pk_add_f32 v[70:71], v[70:71], v[138:139]
	v_pk_add_f32 v[76:77], v[76:77], v[148:149]
	v_pk_add_f32 v[66:67], v[66:67], v[134:135]
	v_pk_add_f32 v[72:73], v[72:73], v[140:141]
	v_pk_add_f32 v[102:103], v[102:103], v[154:155]
	v_pk_add_f32 v[68:69], v[68:69], v[136:137]
	v_pk_add_f32 v[64:65], v[64:65], v[156:157]
	v_pk_add_f32 v[56:57], v[56:57], v[140:141]
	v_pk_add_f32 v[46:47], v[46:47], v[134:135]
	v_pk_add_f32 v[62:63], v[62:63], v[154:155]
	v_pk_add_f32 v[52:53], v[52:53], v[156:157]
	v_pk_add_f32 v[60:61], v[60:61], v[148:149]
	v_pk_add_f32 v[58:59], v[58:59], v[146:147]
	v_pk_add_f32 v[54:55], v[54:55], v[138:139]
	v_pk_add_f32 v[48:49], v[48:49], v[136:137]
	v_pk_add_f32 v[42:43], v[42:43], v[146:147]
	v_pk_add_f32 v[38:39], v[38:39], v[138:139]
	v_pk_add_f32 v[44:45], v[44:45], v[148:149]
	v_pk_add_f32 v[30:31], v[30:31], v[134:135]
	v_pk_add_f32 v[40:41], v[40:41], v[140:141]
	v_pk_add_f32 v[50:51], v[50:51], v[154:155]
	s_waitcnt vmcnt(3)
	v_lshlrev_b32_e32 v190, 16, v174
	v_and_b32_e32 v191, 0xffff0000, v174
	v_lshlrev_b32_e32 v174, 16, v175
	v_and_b32_e32 v175, 0xffff0000, v175
	v_pk_mul_f32 v[174:175], v[174:175], s[0:1] op_sel_hi:[1,0]
	s_waitcnt vmcnt(2)
	v_lshlrev_b32_e32 v182, 16, v186
	v_and_b32_e32 v183, 0xffff0000, v186
	v_lshlrev_b32_e32 v184, 16, v187
	v_and_b32_e32 v185, 0xffff0000, v187
	v_lshlrev_b32_e32 v186, 16, v188
	v_and_b32_e32 v187, 0xffff0000, v188
	v_pk_fma_f32 v[112:113], v[152:153], v[112:113], v[174:175]
	v_lshlrev_b32_e32 v174, 16, v177
	v_and_b32_e32 v175, 0xffff0000, v177
	v_pk_mul_f32 v[186:187], v[186:187], s[0:1] op_sel_hi:[1,0]
	v_pk_mul_f32 v[174:175], v[174:175], s[0:1] op_sel_hi:[1,0]
	v_pk_fma_f32 v[118:119], v[158:159], v[118:119], v[186:187]
	v_pk_fma_f32 v[96:97], v[144:145], v[96:97], v[174:175]
	v_add_u32_e32 v174, 0x60, v168
	v_ashrrev_i32_e32 v175, 31, v174
	v_lshlrev_b32_e32 v188, 16, v189
	v_and_b32_e32 v189, 0xffff0000, v189
	v_lshlrev_b32_e32 v192, 16, v176
	v_and_b32_e32 v193, 0xffff0000, v176
	v_lshlrev_b64 v[174:175], 11, v[174:175]
	v_pk_mul_f32 v[182:183], v[182:183], s[0:1] op_sel_hi:[1,0]
	v_pk_mul_f32 v[184:185], v[184:185], s[0:1] op_sel_hi:[1,0]
	v_pk_mul_f32 v[188:189], v[188:189], s[0:1] op_sel_hi:[1,0]
	v_pk_mul_f32 v[190:191], v[190:191], s[0:1] op_sel_hi:[1,0]
	v_pk_mul_f32 v[176:177], v[192:193], s[0:1] op_sel_hi:[1,0]
	v_lshl_add_u64 v[174:175], s[84:85], 0, v[174:175]
	v_pk_fma_f32 v[128:129], v[164:165], v[128:129], v[184:185]
	v_pk_fma_f32 v[126:127], v[162:163], v[126:127], v[182:183]
	v_pk_fma_f32 v[120:121], v[160:161], v[120:121], v[188:189]
	v_pk_fma_f32 v[110:111], v[150:151], v[110:111], v[190:191]
	v_pk_fma_f32 v[94:95], v[142:143], v[94:95], v[176:177]
	v_lshl_add_u64 v[182:183], v[174:175], 0, v[170:171]
	global_load_dwordx4 v[174:177], v[182:183], off offset:256
	s_nop 0
	global_load_dwordx4 v[182:185], v[182:183], off
	v_pk_add_f32 v[32:33], v[32:33], v[136:137]
	v_pk_add_f32 v[34:35], v[34:35], v[154:155]
	v_pk_add_f32 v[26:27], v[26:27], v[146:147]
	v_pk_add_f32 v[24:25], v[24:25], v[140:141]
	v_pk_add_f32 v[14:15], v[14:15], v[134:135]
	v_pk_add_f32 v[20:21], v[20:21], v[156:157]
	v_pk_add_f32 v[12:13], v[12:13], v[148:149]
	v_pk_add_f32 v[10:11], v[10:11], v[146:147]
	s_waitcnt vmcnt(3)
	v_lshlrev_b32_e32 v186, 16, v130
	v_and_b32_e32 v187, 0xffff0000, v130
	v_lshlrev_b32_e32 v130, 16, v131
	v_and_b32_e32 v131, 0xffff0000, v131
	v_pk_mul_f32 v[130:131], v[130:131], s[0:1] op_sel_hi:[1,0]
	v_pk_mul_f32 v[186:187], v[186:187], s[0:1] op_sel_hi:[1,0]
	v_pk_fma_f32 v[104:105], v[164:165], v[104:105], v[130:131]
	v_lshlrev_b32_e32 v130, 16, v132
	v_and_b32_e32 v131, 0xffff0000, v132
	v_pk_mul_f32 v[130:131], v[130:131], s[0:1] op_sel_hi:[1,0]
	v_lshlrev_b32_e32 v132, 16, v133
	v_pk_fma_f32 v[74:75], v[158:159], v[74:75], v[130:131]
	s_waitcnt vmcnt(2)
	v_lshlrev_b32_e32 v130, 16, v178
	v_and_b32_e32 v131, 0xffff0000, v178
	v_pk_mul_f32 v[130:131], v[130:131], s[0:1] op_sel_hi:[1,0]
	v_and_b32_e32 v133, 0xffff0000, v133
	v_pk_fma_f32 v[70:71], v[150:151], v[70:71], v[130:131]
	v_lshlrev_b32_e32 v130, 16, v180
	v_and_b32_e32 v131, 0xffff0000, v180
	v_pk_mul_f32 v[132:133], v[132:133], s[0:1] op_sel_hi:[1,0]
	v_pk_mul_f32 v[130:131], v[130:131], s[0:1] op_sel_hi:[1,0]
	v_pk_fma_f32 v[76:77], v[160:161], v[76:77], v[132:133]
	v_lshlrev_b32_e32 v132, 16, v179
	v_and_b32_e32 v133, 0xffff0000, v179
	v_pk_fma_f32 v[66:67], v[142:143], v[66:67], v[130:131]
	v_add_u32_e32 v130, 0x70, v168
	v_pk_mul_f32 v[132:133], v[132:133], s[0:1] op_sel_hi:[1,0]
	v_ashrrev_i32_e32 v131, 31, v130
	v_pk_fma_f32 v[72:73], v[152:153], v[72:73], v[132:133]
	v_lshlrev_b32_e32 v132, 16, v181
	v_and_b32_e32 v133, 0xffff0000, v181
	v_lshlrev_b64 v[130:131], 11, v[130:131]
	v_pk_mul_f32 v[132:133], v[132:133], s[0:1] op_sel_hi:[1,0]
	v_lshl_add_u64 v[130:131], s[84:85], 0, v[130:131]
	v_pk_fma_f32 v[102:103], v[162:163], v[102:103], v[186:187]
	v_pk_fma_f32 v[68:69], v[144:145], v[68:69], v[132:133]
	v_lshl_add_u64 v[178:179], v[130:131], 0, v[170:171]
	s_cmp_eq_u32 s100, 4
	s_cbranch_scc0 .Lp9_gate_4
	global_load_dwordx4 v[162:165], v[240:241], off
	global_load_dwordx4 v[158:161], v[240:241], off offset:16
	global_load_dwordx4 v[150:153], v[240:241], off offset:512
	global_load_dwordx4 v[142:145], v[240:241], off offset:528
	s_waitcnt vmcnt(0)
.Lp9_gate_4:
	global_load_dwordx4 v[130:133], v[178:179], off
	s_nop 0
	global_load_dwordx4 v[178:181], v[178:179], off offset:256
	v_pk_add_f32 v[36:37], v[36:37], v[156:157]
	v_pk_add_f32 v[8:9], v[8:9], v[140:141]
	v_pk_add_f32 v[6:7], v[6:7], v[138:139]
	v_pk_add_f32 v[28:29], v[28:29], v[148:149]
	v_pk_add_f32 v[22:23], v[22:23], v[138:139]
	v_pk_add_f32 v[16:17], v[16:17], v[136:137]
	v_pk_add_f32 v[18:19], v[18:19], v[154:155]
	v_pk_add_f32 v[4:5], v[4:5], v[136:137]
	v_pk_add_f32 v[2:3], v[2:3], v[134:135]
	v_lshl_add_u64 v[134:135], s[48:49], 0, v[166:167]
	s_waitcnt vmcnt(2)
	v_lshlrev_b32_e32 v186, 16, v182
	v_and_b32_e32 v187, 0xffff0000, v182
	v_lshlrev_b32_e32 v182, 16, v183
	v_and_b32_e32 v183, 0xffff0000, v183
	v_pk_mul_f32 v[182:183], v[182:183], s[0:1] op_sel_hi:[1,0]
	v_pk_mul_f32 v[186:187], v[186:187], s[0:1] op_sel_hi:[1,0]
	v_pk_fma_f32 v[64:65], v[164:165], v[64:65], v[182:183]
	v_lshlrev_b32_e32 v182, 16, v174
	v_and_b32_e32 v183, 0xffff0000, v174
	v_lshlrev_b32_e32 v174, 16, v175
	v_and_b32_e32 v175, 0xffff0000, v175
	v_pk_mul_f32 v[174:175], v[174:175], s[0:1] op_sel_hi:[1,0]
	v_pk_fma_f32 v[62:63], v[162:163], v[62:63], v[186:187]
	v_pk_fma_f32 v[56:57], v[152:153], v[56:57], v[174:175]
	v_lshlrev_b32_e32 v174, 16, v176
	v_and_b32_e32 v175, 0xffff0000, v176
	v_pk_mul_f32 v[174:175], v[174:175], s[0:1] op_sel_hi:[1,0]
	v_lshlrev_b32_e32 v188, 16, v184
	v_pk_fma_f32 v[46:47], v[142:143], v[46:47], v[174:175]
	v_add_u32_e32 v174, 0x80, v168
	v_ashrrev_i32_e32 v175, 31, v174
	v_and_b32_e32 v189, 0xffff0000, v184
	v_lshlrev_b32_e32 v184, 16, v185
	v_and_b32_e32 v185, 0xffff0000, v185
	v_lshlrev_b32_e32 v176, 16, v177
	v_and_b32_e32 v177, 0xffff0000, v177
	v_lshlrev_b64 v[174:175], 11, v[174:175]
	v_pk_mul_f32 v[188:189], v[188:189], s[0:1] op_sel_hi:[1,0]
	v_pk_mul_f32 v[184:185], v[184:185], s[0:1] op_sel_hi:[1,0]
	v_pk_mul_f32 v[182:183], v[182:183], s[0:1] op_sel_hi:[1,0]
	v_pk_mul_f32 v[176:177], v[176:177], s[0:1] op_sel_hi:[1,0]
	v_lshl_add_u64 v[174:175], s[84:85], 0, v[174:175]
	v_pk_fma_f32 v[60:61], v[160:161], v[60:61], v[184:185]
	v_pk_fma_f32 v[58:59], v[158:159], v[58:59], v[188:189]
	v_pk_fma_f32 v[54:55], v[150:151], v[54:55], v[182:183]
	v_pk_fma_f32 v[48:49], v[144:145], v[48:49], v[176:177]
	v_lshl_add_u64 v[182:183], v[174:175], 0, v[170:171]
	global_load_dwordx4 v[174:177], v[182:183], off offset:256
	s_nop 0
	global_load_dwordx4 v[182:185], v[182:183], off
	s_waitcnt vmcnt(3)
	v_lshlrev_b32_e32 v186, 16, v130
	v_and_b32_e32 v187, 0xffff0000, v130
	v_lshlrev_b32_e32 v130, 16, v131
	v_and_b32_e32 v131, 0xffff0000, v131
	v_pk_mul_f32 v[130:131], v[130:131], s[0:1] op_sel_hi:[1,0]
	v_pk_mul_f32 v[186:187], v[186:187], s[0:1] op_sel_hi:[1,0]
	v_pk_fma_f32 v[52:53], v[164:165], v[52:53], v[130:131]
	v_lshlrev_b32_e32 v130, 16, v132
	v_and_b32_e32 v131, 0xffff0000, v132
	v_pk_mul_f32 v[130:131], v[130:131], s[0:1] op_sel_hi:[1,0]
	v_lshlrev_b32_e32 v132, 16, v133
	v_pk_fma_f32 v[42:43], v[158:159], v[42:43], v[130:131]
	s_waitcnt vmcnt(2)
	v_lshlrev_b32_e32 v130, 16, v178
	v_and_b32_e32 v131, 0xffff0000, v178
	v_pk_mul_f32 v[130:131], v[130:131], s[0:1] op_sel_hi:[1,0]
	v_and_b32_e32 v133, 0xffff0000, v133
	v_pk_fma_f32 v[38:39], v[150:151], v[38:39], v[130:131]
	v_lshlrev_b32_e32 v130, 16, v180
	v_and_b32_e32 v131, 0xffff0000, v180
	v_pk_mul_f32 v[132:133], v[132:133], s[0:1] op_sel_hi:[1,0]
	v_pk_mul_f32 v[130:131], v[130:131], s[0:1] op_sel_hi:[1,0]
	v_pk_fma_f32 v[44:45], v[160:161], v[44:45], v[132:133]
	v_lshlrev_b32_e32 v132, 16, v179
	v_and_b32_e32 v133, 0xffff0000, v179
	v_pk_fma_f32 v[30:31], v[142:143], v[30:31], v[130:131]
	v_add_u32_e32 v130, 0xb0, v168
	v_pk_mul_f32 v[132:133], v[132:133], s[0:1] op_sel_hi:[1,0]
	v_ashrrev_i32_e32 v131, 31, v130
	v_pk_fma_f32 v[40:41], v[152:153], v[40:41], v[132:133]
	v_lshlrev_b32_e32 v132, 16, v181
	v_and_b32_e32 v133, 0xffff0000, v181
	v_lshlrev_b64 v[130:131], 11, v[130:131]
	v_pk_mul_f32 v[132:133], v[132:133], s[0:1] op_sel_hi:[1,0]
	v_lshl_add_u64 v[130:131], s[84:85], 0, v[130:131]
	v_pk_fma_f32 v[50:51], v[162:163], v[50:51], v[186:187]
	v_pk_fma_f32 v[32:33], v[144:145], v[32:33], v[132:133]
	v_lshl_add_u64 v[168:169], v[130:131], 0, v[170:171]
	s_cmp_eq_u32 s100, 6
	s_cbranch_scc0 .Lp9_gate_6
	global_load_dwordx4 v[162:165], v[240:241], off
	global_load_dwordx4 v[158:161], v[240:241], off offset:16
	global_load_dwordx4 v[150:153], v[240:241], off offset:512
	global_load_dwordx4 v[142:145], v[240:241], off offset:528
	s_waitcnt vmcnt(0)
.Lp9_gate_6:
	global_load_dwordx4 v[130:133], v[168:169], off
	s_nop 0
	global_load_dwordx4 v[168:171], v[168:169], off offset:256
	s_waitcnt vmcnt(2)
	v_lshlrev_b32_e32 v178, 16, v182
	v_and_b32_e32 v179, 0xffff0000, v182
	v_pk_mul_f32 v[178:179], v[178:179], s[0:1] op_sel_hi:[1,0]
	v_lshlrev_b32_e32 v180, 16, v183
	v_pk_fma_f32 v[34:35], v[162:163], v[34:35], v[178:179]
	v_lshlrev_b32_e32 v178, 16, v184
	v_and_b32_e32 v179, 0xffff0000, v184
	v_pk_mul_f32 v[178:179], v[178:179], s[0:1] op_sel_hi:[1,0]
	v_and_b32_e32 v181, 0xffff0000, v183
	v_pk_fma_f32 v[26:27], v[158:159], v[26:27], v[178:179]
	v_lshlrev_b32_e32 v178, 16, v174
	v_and_b32_e32 v179, 0xffff0000, v174
	v_lshlrev_b32_e32 v174, 16, v175
	v_and_b32_e32 v175, 0xffff0000, v175
	v_pk_mul_f32 v[174:175], v[174:175], s[0:1] op_sel_hi:[1,0]
	v_pk_mul_f32 v[180:181], v[180:181], s[0:1] op_sel_hi:[1,0]
	v_pk_fma_f32 v[24:25], v[152:153], v[24:25], v[174:175]
	v_lshlrev_b32_e32 v174, 16, v176
	v_and_b32_e32 v175, 0xffff0000, v176
	v_pk_mul_f32 v[174:175], v[174:175], s[0:1] op_sel_hi:[1,0]
	v_pk_fma_f32 v[36:37], v[164:165], v[36:37], v[180:181]
	v_pk_fma_f32 v[14:15], v[142:143], v[14:15], v[174:175]
	v_lshlrev_b32_e32 v180, 16, v185
	v_and_b32_e32 v181, 0xffff0000, v185
	v_lshlrev_b32_e32 v176, 16, v177
	v_and_b32_e32 v177, 0xffff0000, v177
	v_pk_mul_f32 v[180:181], v[180:181], s[0:1] op_sel_hi:[1,0]
	v_pk_mul_f32 v[178:179], v[178:179], s[0:1] op_sel_hi:[1,0]
	v_pk_mul_f32 v[176:177], v[176:177], s[0:1] op_sel_hi:[1,0]
	v_pk_fma_f32 v[28:29], v[160:161], v[28:29], v[180:181]
	v_pk_fma_f32 v[22:23], v[150:151], v[22:23], v[178:179]
	v_pk_fma_f32 v[16:17], v[144:145], v[16:17], v[176:177]
	s_waitcnt vmcnt(1)
	v_lshlrev_b32_e32 v174, 16, v130
	v_and_b32_e32 v175, 0xffff0000, v130
	v_lshlrev_b32_e32 v130, 16, v131
	v_and_b32_e32 v131, 0xffff0000, v131
	v_pk_mul_f32 v[130:131], v[130:131], s[0:1] op_sel_hi:[1,0]
	v_pk_mul_f32 v[174:175], v[174:175], s[0:1] op_sel_hi:[1,0]
	v_pk_fma_f32 v[20:21], v[164:165], v[20:21], v[130:131]
	v_lshlrev_b32_e32 v130, 16, v132
	v_and_b32_e32 v131, 0xffff0000, v132
	v_lshlrev_b32_e32 v132, 16, v133
	v_and_b32_e32 v133, 0xffff0000, v133
	v_pk_mul_f32 v[130:131], v[130:131], s[0:1] op_sel_hi:[1,0]
	v_pk_mul_f32 v[132:133], v[132:133], s[0:1] op_sel_hi:[1,0]
	v_pk_fma_f32 v[10:11], v[158:159], v[10:11], v[130:131]
	v_pk_fma_f32 v[12:13], v[160:161], v[12:13], v[132:133]
	s_waitcnt vmcnt(0)
	v_lshlrev_b32_e32 v130, 16, v168
	v_and_b32_e32 v131, 0xffff0000, v168
	v_lshlrev_b32_e32 v132, 16, v169
	v_and_b32_e32 v133, 0xffff0000, v169
	v_pk_mul_f32 v[130:131], v[130:131], s[0:1] op_sel_hi:[1,0]
	v_pk_mul_f32 v[132:133], v[132:133], s[0:1] op_sel_hi:[1,0]
	v_pk_fma_f32 v[6:7], v[150:151], v[6:7], v[130:131]
	v_pk_fma_f32 v[8:9], v[152:153], v[8:9], v[132:133]
	v_lshlrev_b32_e32 v130, 16, v170
	v_and_b32_e32 v131, 0xffff0000, v170
	v_lshlrev_b32_e32 v132, 16, v171
	v_and_b32_e32 v133, 0xffff0000, v171
	v_pk_mul_f32 v[130:131], v[130:131], s[0:1] op_sel_hi:[1,0]
	v_pk_mul_f32 v[132:133], v[132:133], s[0:1] op_sel_hi:[1,0]
	v_pk_fma_f32 v[18:19], v[162:163], v[18:19], v[174:175]
	v_pk_fma_f32 v[4:5], v[144:145], v[4:5], v[132:133]
	v_pk_fma_f32 v[2:3], v[142:143], v[2:3], v[130:131]
	v_lshl_add_u64 v[142:143], s[50:51], 0, v[166:167]
	global_load_dwordx4 v[146:149], v[134:135], off offset:16
	global_load_dwordx4 v[154:157], v[134:135], off
	global_load_dwordx4 v[130:133], v[134:135], off offset:528
	global_load_dwordx4 v[138:141], v[134:135], off offset:512
	global_load_dwordx4 v[150:153], v[142:143], off offset:16
	global_load_dwordx4 v[158:161], v[142:143], off
	s_nop 0
	global_load_dwordx4 v[134:137], v[142:143], off offset:528
	s_nop 0
	global_load_dwordx4 v[142:145], v[142:143], off offset:512
	v_mbcnt_lo_u32_b32 v162, -1, 0
	v_mbcnt_hi_u32_b32 v163, -1, v162
	v_and_b32_e32 v164, 64, v163
	v_add_u32_e32 v173, 64, v164
	v_mov_b32_e32 v164, v123
	v_mov_b32_e32 v165, v124
	v_mov_b32_e32 v168, v122
	v_mov_b32_e32 v169, v125
	v_pk_add_f32 v[164:165], v[164:165], v[168:169]
	v_mov_b32_e32 v168, v115
	v_mov_b32_e32 v169, v116
	v_mov_b32_e32 v170, v114
	v_mov_b32_e32 v171, v117
	v_pk_add_f32 v[168:169], v[168:169], v[170:171]
	v_add_f32_e32 v164, v164, v165
	v_pk_add_f32 v[168:169], v[168:169], v[168:169] op_sel_hi:[0,1]
	v_xor_b32_e32 v162, 16, v163
	v_add_f32_e32 v165, 0, v164
	v_add_f32_e32 v171, v106, v107
	v_add_f32_e32 v175, v108, v109
	v_mov_b32_e32 v170, v98
	v_mov_b32_e32 v174, v99
	v_mov_b32_e32 v168, v100
	v_mov_b32_e32 v164, v101
	v_cmp_lt_i32_e32 vcc, v162, v173
	v_pk_add_f32 v[170:171], v[170:171], v[174:175]
	v_pk_add_f32 v[164:165], v[168:169], v[164:165]
	v_cndmask_b32_e32 v162, v163, v162, vcc
	v_pk_add_f32 v[164:165], v[170:171], v[164:165]
	v_lshlrev_b32_e32 v162, 2, v162
	v_add_f32_e32 v165, v164, v165
	ds_bpermute_b32 v168, v162, v165
	v_xor_b32_e32 v164, 32, v163
	v_cmp_lt_i32_e32 vcc, v164, v173
	s_lshl_b32 s0, s7, 3
	s_add_i32 s2, s0, 0
	v_cndmask_b32_e32 v163, v163, v164, vcc
	v_lshlrev_b32_e32 v164, 2, v163
	s_waitcnt lgkmcnt(0)
	v_add_f32_e32 v163, v165, v168
	ds_bpermute_b32 v165, v164, v163
	s_waitcnt lgkmcnt(0)
	v_add_f32_e32 v165, v163, v165
	v_fmamk_f32 v168, v165, 0xbc800000, v125
	v_fmamk_f32 v170, v165, 0xbc800000, v123
	v_fmamk_f32 v163, v165, 0xbc800000, v124
	v_fmamk_f32 v169, v165, 0xbc800000, v122
	v_mul_f32_e32 v170, v170, v170
	v_mul_f32_e32 v168, v168, v168
	v_fmac_f32_e32 v170, v169, v169
	v_fmac_f32_e32 v168, v163, v163
	v_fmamk_f32 v169, v165, 0xbc800000, v117
	v_fmamk_f32 v171, v165, 0xbc800000, v115
	v_add_f32_e32 v163, v170, v168
	v_fmamk_f32 v168, v165, 0xbc800000, v116
	v_fmamk_f32 v170, v165, 0xbc800000, v114
	v_mul_f32_e32 v171, v171, v171
	v_mul_f32_e32 v169, v169, v169
	v_fmac_f32_e32 v171, v170, v170
	v_fmac_f32_e32 v169, v168, v168
	v_add_f32_e32 v168, v171, v169
	v_fmamk_f32 v169, v165, 0xbc800000, v109
	v_fmamk_f32 v171, v165, 0xbc800000, v107
	v_add_f32_e32 v163, v163, v168
	v_fmamk_f32 v168, v165, 0xbc800000, v108
	v_fmamk_f32 v170, v165, 0xbc800000, v106
	v_mul_f32_e32 v171, v171, v171
	v_mul_f32_e32 v169, v169, v169
	v_fmac_f32_e32 v171, v170, v170
	v_fmac_f32_e32 v169, v168, v168
	v_add_f32_e32 v168, v171, v169
	v_fmamk_f32 v169, v165, 0xbc800000, v101
	v_fmamk_f32 v171, v165, 0xbc800000, v99
	v_add_f32_e32 v163, v168, v163
	v_fmamk_f32 v168, v165, 0xbc800000, v100
	v_fmamk_f32 v170, v165, 0xbc800000, v98
	v_mul_f32_e32 v171, v171, v171
	v_mul_f32_e32 v169, v169, v169
	v_fmac_f32_e32 v171, v170, v170
	v_fmac_f32_e32 v169, v168, v168
	v_add_f32_e32 v168, v171, v169
	v_add_f32_e32 v163, v168, v163
	ds_bpermute_b32 v168, v162, v163
	s_waitcnt lgkmcnt(0)
	v_add_f32_e32 v168, v163, v168
	ds_bpermute_b32 v169, v164, v168
	v_and_b32_e32 v163, 63, v0
	v_cmp_gt_u32_e32 vcc, 16, v163
	s_and_saveexec_b64 s[0:1], vcc
	s_cbranch_execz .LBB0_656
	s_lshl_b32 s4, s11, 11
	s_add_i32 s4, s2, s4
	v_mul_f32_e32 v170, 0x3c800000, v165
	v_lshl_add_u32 v165, v1, 5, s4
	s_waitcnt lgkmcnt(0)
	v_add_f32_e32 v171, v168, v169
	ds_write_b64 v165, v[170:171]

.LBB0_694:
	s_or_b64 exec, exec, s[2:3]
	s_waitcnt lgkmcnt(0)
	s_barrier
	v_lshl_add_u32 v162, v172, 3, 0
	ds_read_b64 v[164:165], v162 offset:8192
	v_add_u32_e32 v0, s99, v172
	v_ashrrev_i32_e32 v1, 31, v0
	v_lshlrev_b64 v[168:169], 12, v[0:1]
	v_lshl_add_u64 v[168:169], s[52:53], 0, v[168:169]
	s_waitcnt lgkmcnt(0)
	v_sub_f32_e32 v125, v125, v164
	v_sub_f32_e32 v124, v124, v164
	v_sub_f32_e32 v123, v123, v164
	v_sub_f32_e32 v122, v122, v164
	v_sub_f32_e32 v117, v117, v164
	v_sub_f32_e32 v116, v116, v164
	v_sub_f32_e32 v115, v115, v164
	v_sub_f32_e32 v114, v114, v164
	v_sub_f32_e32 v109, v109, v164
	v_sub_f32_e32 v108, v108, v164
	v_sub_f32_e32 v107, v107, v164
	v_sub_f32_e32 v106, v106, v164
	v_sub_f32_e32 v101, v101, v164
	v_sub_f32_e32 v100, v100, v164
	v_sub_f32_e32 v99, v99, v164
	v_sub_f32_e32 v98, v98, v164
	v_pk_mul_f32 v[122:123], v[164:165], v[122:123] op_sel:[1,0]
	v_pk_mul_f32 v[124:125], v[164:165], v[124:125] op_sel:[1,0]
	v_pk_mul_f32 v[114:115], v[164:165], v[114:115] op_sel:[1,0]
	v_pk_mul_f32 v[116:117], v[164:165], v[116:117] op_sel:[1,0]
	v_pk_mul_f32 v[106:107], v[164:165], v[106:107] op_sel:[1,0]
	v_pk_mul_f32 v[108:109], v[164:165], v[108:109] op_sel:[1,0]
	v_pk_mul_f32 v[98:99], v[164:165], v[98:99] op_sel:[1,0]
	v_pk_mul_f32 v[100:101], v[164:165], v[100:101] op_sel:[1,0]
	s_waitcnt vmcnt(2)
	v_pk_fma_f32 v[124:125], v[156:157], v[124:125], v[160:161]
	v_pk_fma_f32 v[122:123], v[154:155], v[122:123], v[158:159]
	v_lshl_add_u64 v[168:169], v[168:169], 0, v[166:167]
	v_pk_fma_f32 v[116:117], v[148:149], v[116:117], v[152:153]
	v_pk_fma_f32 v[114:115], v[146:147], v[114:115], v[150:151]
	s_waitcnt vmcnt(0)
	v_pk_fma_f32 v[108:109], v[140:141], v[108:109], v[144:145]
	v_pk_fma_f32 v[106:107], v[138:139], v[106:107], v[142:143]
	v_pk_fma_f32 v[100:101], v[132:133], v[100:101], v[136:137]
	v_pk_fma_f32 v[98:99], v[130:131], v[98:99], v[134:135]
	global_store_dwordx4 v[168:169], v[122:125], off
	global_store_dwordx4 v[168:169], v[114:117], off offset:16
	global_store_dwordx4 v[168:169], v[106:109], off offset:512
	global_store_dwordx4 v[168:169], v[98:101], off offset:528
	ds_read_b64 v[98:99], v162 offset:8320
	s_waitcnt lgkmcnt(0)
	v_sub_f32_e32 v81, v81, v98
	v_add_u32_e32 v100, 16, v0
	v_ashrrev_i32_e32 v101, 31, v100
	v_lshlrev_b64 v[100:101], 12, v[100:101]
	v_sub_f32_e32 v80, v80, v98
	v_sub_f32_e32 v79, v79, v98
	v_sub_f32_e32 v78, v78, v98
	v_sub_f32_e32 v85, v85, v98
	v_sub_f32_e32 v84, v84, v98
	v_sub_f32_e32 v83, v83, v98
	v_sub_f32_e32 v82, v82, v98
	v_lshl_add_u64 v[100:101], s[52:53], 0, v[100:101]
	v_pk_mul_f32 v[78:79], v[98:99], v[78:79] op_sel:[1,0]
	v_pk_mul_f32 v[80:81], v[98:99], v[80:81] op_sel:[1,0]
	v_pk_mul_f32 v[82:83], v[98:99], v[82:83] op_sel:[1,0]
	v_pk_mul_f32 v[84:85], v[98:99], v[84:85] op_sel:[1,0]
	v_lshl_add_u64 v[100:101], v[100:101], 0, v[166:167]
	v_pk_fma_f32 v[80:81], v[148:149], v[80:81], v[152:153]
	v_pk_fma_f32 v[78:79], v[146:147], v[78:79], v[150:151]
	v_pk_fma_f32 v[84:85], v[156:157], v[84:85], v[160:161]
	v_pk_fma_f32 v[82:83], v[154:155], v[82:83], v[158:159]
	global_store_dwordx4 v[100:101], v[78:81], off offset:16
	global_store_dwordx4 v[100:101], v[82:85], off
	s_nop 0
	v_sub_f32_e32 v79, v89, v98
	v_sub_f32_e32 v78, v88, v98
	v_sub_f32_e32 v81, v87, v98
	v_sub_f32_e32 v80, v86, v98
	v_pk_mul_f32 v[82:83], v[98:99], v[80:81] op_sel:[1,0]
	v_pk_mul_f32 v[78:79], v[98:99], v[78:79] op_sel:[1,0]
	s_nop 0
	v_pk_fma_f32 v[80:81], v[140:141], v[78:79], v[144:145]
	v_pk_fma_f32 v[78:79], v[138:139], v[82:83], v[142:143]
	global_store_dwordx4 v[100:101], v[78:81], off offset:512
	s_nop 1
	v_sub_f32_e32 v79, v93, v98
	v_sub_f32_e32 v78, v92, v98
	v_sub_f32_e32 v81, v91, v98
	v_sub_f32_e32 v80, v90, v98
	v_pk_mul_f32 v[82:83], v[98:99], v[80:81] op_sel:[1,0]
	v_pk_mul_f32 v[78:79], v[98:99], v[78:79] op_sel:[1,0]
	s_nop 0
	v_pk_fma_f32 v[80:81], v[132:133], v[78:79], v[136:137]
	v_pk_fma_f32 v[78:79], v[130:131], v[82:83], v[134:135]
	global_store_dwordx4 v[100:101], v[78:81], off offset:528
	ds_read_b64 v[82:83], v162 offset:8448
	s_nop 0
	v_add_u32_e32 v78, 32, v0
	v_ashrrev_i32_e32 v79, 31, v78
	v_lshlrev_b64 v[84:85], 12, v[78:79]
	s_waitcnt lgkmcnt(0)
	v_sub_f32_e32 v79, v129, v82
	v_sub_f32_e32 v78, v128, v82
	v_sub_f32_e32 v81, v127, v82
	v_sub_f32_e32 v80, v126, v82
	v_pk_mul_f32 v[86:87], v[82:83], v[80:81] op_sel:[1,0]
	v_pk_mul_f32 v[78:79], v[82:83], v[78:79] op_sel:[1,0]
	v_lshl_add_u64 v[84:85], s[52:53], 0, v[84:85]
	v_pk_fma_f32 v[80:81], v[156:157], v[78:79], v[160:161]
	v_pk_fma_f32 v[78:79], v[154:155], v[86:87], v[158:159]
	v_lshl_add_u64 v[84:85], v[84:85], 0, v[166:167]
	global_store_dwordx4 v[84:85], v[78:81], off
	s_nop 1
	v_sub_f32_e32 v79, v121, v82
	v_sub_f32_e32 v78, v120, v82
	v_sub_f32_e32 v81, v119, v82
	v_sub_f32_e32 v80, v118, v82
	v_pk_mul_f32 v[86:87], v[82:83], v[80:81] op_sel:[1,0]
	v_pk_mul_f32 v[78:79], v[82:83], v[78:79] op_sel:[1,0]
	s_nop 0
	v_pk_fma_f32 v[80:81], v[148:149], v[78:79], v[152:153]
	v_pk_fma_f32 v[78:79], v[146:147], v[86:87], v[150:151]
	global_store_dwordx4 v[84:85], v[78:81], off offset:16
	s_nop 1
	v_sub_f32_e32 v79, v113, v82
	v_sub_f32_e32 v78, v112, v82
	v_sub_f32_e32 v81, v111, v82
	v_sub_f32_e32 v80, v110, v82
	v_pk_mul_f32 v[86:87], v[82:83], v[80:81] op_sel:[1,0]
	v_pk_mul_f32 v[78:79], v[82:83], v[78:79] op_sel:[1,0]
	s_nop 0
	v_pk_fma_f32 v[80:81], v[140:141], v[78:79], v[144:145]
	v_pk_fma_f32 v[78:79], v[138:139], v[86:87], v[142:143]
	global_store_dwordx4 v[84:85], v[78:81], off offset:512
	s_nop 1
	v_sub_f32_e32 v79, v97, v82
	v_sub_f32_e32 v78, v96, v82
	v_sub_f32_e32 v81, v95, v82
	v_sub_f32_e32 v80, v94, v82
	v_pk_mul_f32 v[86:87], v[82:83], v[80:81] op_sel:[1,0]
	v_pk_mul_f32 v[78:79], v[82:83], v[78:79] op_sel:[1,0]
	s_nop 0
	v_pk_fma_f32 v[80:81], v[132:133], v[78:79], v[136:137]
	v_pk_fma_f32 v[78:79], v[130:131], v[86:87], v[134:135]
	global_store_dwordx4 v[84:85], v[78:81], off offset:528
	ds_read_b64 v[82:83], v162 offset:8576
	s_waitcnt lgkmcnt(0)
	v_sub_f32_e32 v77, v77, v82
	v_add_u32_e32 v78, 48, v0
	v_ashrrev_i32_e32 v79, 31, v78
	v_lshlrev_b64 v[84:85], 12, v[78:79]
	v_sub_f32_e32 v79, v105, v82
	v_sub_f32_e32 v78, v104, v82
	v_sub_f32_e32 v81, v103, v82
	v_sub_f32_e32 v80, v102, v82
	v_sub_f32_e32 v76, v76, v82
	v_sub_f32_e32 v75, v75, v82
	v_sub_f32_e32 v74, v74, v82
	v_sub_f32_e32 v73, v73, v82
	v_sub_f32_e32 v72, v72, v82
	v_sub_f32_e32 v71, v71, v82
	v_sub_f32_e32 v70, v70, v82
	v_sub_f32_e32 v69, v69, v82
	v_sub_f32_e32 v68, v68, v82
	v_sub_f32_e32 v67, v67, v82
	v_sub_f32_e32 v66, v66, v82
	v_pk_mul_f32 v[86:87], v[82:83], v[80:81] op_sel:[1,0]
	v_pk_mul_f32 v[78:79], v[82:83], v[78:79] op_sel:[1,0]
	v_lshl_add_u64 v[84:85], s[52:53], 0, v[84:85]
	v_pk_mul_f32 v[74:75], v[82:83], v[74:75] op_sel:[1,0]
	v_pk_mul_f32 v[76:77], v[82:83], v[76:77] op_sel:[1,0]
	v_pk_mul_f32 v[70:71], v[82:83], v[70:71] op_sel:[1,0]
	v_pk_mul_f32 v[72:73], v[82:83], v[72:73] op_sel:[1,0]
	v_pk_mul_f32 v[66:67], v[82:83], v[66:67] op_sel:[1,0]
	v_pk_mul_f32 v[68:69], v[82:83], v[68:69] op_sel:[1,0]
	v_pk_fma_f32 v[80:81], v[156:157], v[78:79], v[160:161]
	v_pk_fma_f32 v[78:79], v[154:155], v[86:87], v[158:159]
	v_lshl_add_u64 v[84:85], v[84:85], 0, v[166:167]
	v_pk_fma_f32 v[76:77], v[148:149], v[76:77], v[152:153]
	v_pk_fma_f32 v[74:75], v[146:147], v[74:75], v[150:151]
	v_pk_fma_f32 v[72:73], v[140:141], v[72:73], v[144:145]
	v_pk_fma_f32 v[70:71], v[138:139], v[70:71], v[142:143]
	v_pk_fma_f32 v[68:69], v[132:133], v[68:69], v[136:137]
	v_pk_fma_f32 v[66:67], v[130:131], v[66:67], v[134:135]
	ds_read_b64 v[66:67], v162 offset:9216
	s_waitcnt lgkmcnt(0)
	v_sub_f32_e32 v65, v65, v66
	v_add_u32_e32 v68, 0x60, v0
	v_ashrrev_i32_e32 v69, 31, v68
	v_lshlrev_b64 v[68:69], 12, v[68:69]
	v_sub_f32_e32 v64, v64, v66
	v_sub_f32_e32 v63, v63, v66
	v_sub_f32_e32 v62, v62, v66
	v_sub_f32_e32 v61, v61, v66
	v_sub_f32_e32 v60, v60, v66
	v_sub_f32_e32 v59, v59, v66
	v_sub_f32_e32 v58, v58, v66
	v_sub_f32_e32 v57, v57, v66
	v_sub_f32_e32 v56, v56, v66
	v_sub_f32_e32 v55, v55, v66
	v_sub_f32_e32 v54, v54, v66
	v_sub_f32_e32 v49, v49, v66
	v_sub_f32_e32 v48, v48, v66
	v_sub_f32_e32 v47, v47, v66
	v_sub_f32_e32 v46, v46, v66
	v_pk_mul_f32 v[62:63], v[66:67], v[62:63] op_sel:[1,0]
	v_pk_mul_f32 v[64:65], v[66:67], v[64:65] op_sel:[1,0]
	v_lshl_add_u64 v[68:69], s[52:53], 0, v[68:69]
	v_pk_mul_f32 v[58:59], v[66:67], v[58:59] op_sel:[1,0]
	v_pk_mul_f32 v[60:61], v[66:67], v[60:61] op_sel:[1,0]
	v_pk_mul_f32 v[54:55], v[66:67], v[54:55] op_sel:[1,0]
	v_pk_mul_f32 v[56:57], v[66:67], v[56:57] op_sel:[1,0]
	v_pk_mul_f32 v[46:47], v[66:67], v[46:47] op_sel:[1,0]
	v_pk_mul_f32 v[48:49], v[66:67], v[48:49] op_sel:[1,0]
	v_pk_fma_f32 v[64:65], v[156:157], v[64:65], v[160:161]
	v_pk_fma_f32 v[62:63], v[154:155], v[62:63], v[158:159]
	v_lshl_add_u64 v[68:69], v[68:69], 0, v[166:167]
	v_pk_fma_f32 v[60:61], v[148:149], v[60:61], v[152:153]
	v_pk_fma_f32 v[58:59], v[146:147], v[58:59], v[150:151]
	v_pk_fma_f32 v[56:57], v[140:141], v[56:57], v[144:145]
	v_pk_fma_f32 v[54:55], v[138:139], v[54:55], v[142:143]
	v_pk_fma_f32 v[48:49], v[132:133], v[48:49], v[136:137]
	v_pk_fma_f32 v[46:47], v[130:131], v[46:47], v[134:135]
	global_store_dwordx4 v[68:69], v[62:65], off
	global_store_dwordx4 v[68:69], v[58:61], off offset:16
	global_store_dwordx4 v[68:69], v[54:57], off offset:512
	global_store_dwordx4 v[68:69], v[46:49], off offset:528
	ds_read_b64 v[54:55], v162 offset:9344
	s_waitcnt lgkmcnt(0)
	v_sub_f32_e32 v45, v45, v54
	v_add_u32_e32 v46, 0x70, v0
	v_ashrrev_i32_e32 v47, 31, v46
	v_lshlrev_b64 v[56:57], 12, v[46:47]
	v_sub_f32_e32 v47, v53, v54
	v_sub_f32_e32 v46, v52, v54
	v_sub_f32_e32 v49, v51, v54
	v_sub_f32_e32 v48, v50, v54
	v_pk_mul_f32 v[50:51], v[54:55], v[48:49] op_sel:[1,0]
	v_pk_mul_f32 v[46:47], v[54:55], v[46:47] op_sel:[1,0]
	v_sub_f32_e32 v44, v44, v54
	v_sub_f32_e32 v43, v43, v54
	v_sub_f32_e32 v42, v42, v54
	v_sub_f32_e32 v41, v41, v54
	v_sub_f32_e32 v40, v40, v54
	v_sub_f32_e32 v39, v39, v54
	v_sub_f32_e32 v38, v38, v54
	v_sub_f32_e32 v33, v33, v54
	v_sub_f32_e32 v32, v32, v54
	v_sub_f32_e32 v31, v31, v54
	v_sub_f32_e32 v30, v30, v54
	v_pk_fma_f32 v[48:49], v[156:157], v[46:47], v[160:161]
	v_pk_fma_f32 v[46:47], v[154:155], v[50:51], v[158:159]
	v_lshl_add_u64 v[50:51], s[52:53], 0, v[56:57]
	v_pk_mul_f32 v[42:43], v[54:55], v[42:43] op_sel:[1,0]
	v_pk_mul_f32 v[44:45], v[54:55], v[44:45] op_sel:[1,0]
	v_pk_mul_f32 v[38:39], v[54:55], v[38:39] op_sel:[1,0]
	v_pk_mul_f32 v[40:41], v[54:55], v[40:41] op_sel:[1,0]
	v_pk_mul_f32 v[30:31], v[54:55], v[30:31] op_sel:[1,0]
	v_pk_mul_f32 v[32:33], v[54:55], v[32:33] op_sel:[1,0]
	v_lshl_add_u64 v[50:51], v[50:51], 0, v[166:167]
	v_pk_fma_f32 v[44:45], v[148:149], v[44:45], v[152:153]
	v_pk_fma_f32 v[42:43], v[146:147], v[42:43], v[150:151]
	v_pk_fma_f32 v[40:41], v[140:141], v[40:41], v[144:145]
	v_pk_fma_f32 v[38:39], v[138:139], v[38:39], v[142:143]
	v_pk_fma_f32 v[32:33], v[132:133], v[32:33], v[136:137]
	v_pk_fma_f32 v[30:31], v[130:131], v[30:31], v[134:135]
	global_store_dwordx4 v[50:51], v[46:49], off
	global_store_dwordx4 v[50:51], v[42:45], off offset:16
	global_store_dwordx4 v[50:51], v[38:41], off offset:512
	global_store_dwordx4 v[50:51], v[30:33], off offset:528
	ds_read_b64 v[38:39], v162 offset:9472
	s_waitcnt lgkmcnt(0)
	v_sub_f32_e32 v29, v29, v38
	v_add_u32_e32 v30, 0x80, v0
	v_ashrrev_i32_e32 v31, 31, v30
	v_lshlrev_b64 v[40:41], 12, v[30:31]
	v_sub_f32_e32 v31, v37, v38
	v_sub_f32_e32 v30, v36, v38
	v_sub_f32_e32 v33, v35, v38
	v_sub_f32_e32 v32, v34, v38
	v_pk_mul_f32 v[34:35], v[38:39], v[32:33] op_sel:[1,0]
	v_pk_mul_f32 v[30:31], v[38:39], v[30:31] op_sel:[1,0]
	v_sub_f32_e32 v28, v28, v38
	v_sub_f32_e32 v27, v27, v38
	v_sub_f32_e32 v26, v26, v38
	v_sub_f32_e32 v25, v25, v38
	v_sub_f32_e32 v24, v24, v38
	v_sub_f32_e32 v23, v23, v38
	v_sub_f32_e32 v22, v22, v38
	v_sub_f32_e32 v17, v17, v38
	v_sub_f32_e32 v16, v16, v38
	v_sub_f32_e32 v15, v15, v38
	v_sub_f32_e32 v14, v14, v38
	v_pk_fma_f32 v[32:33], v[156:157], v[30:31], v[160:161]
	v_pk_fma_f32 v[30:31], v[154:155], v[34:35], v[158:159]
	v_lshl_add_u64 v[34:35], s[52:53], 0, v[40:41]
	v_pk_mul_f32 v[26:27], v[38:39], v[26:27] op_sel:[1,0]
	v_pk_mul_f32 v[28:29], v[38:39], v[28:29] op_sel:[1,0]
	v_pk_mul_f32 v[22:23], v[38:39], v[22:23] op_sel:[1,0]
	v_pk_mul_f32 v[24:25], v[38:39], v[24:25] op_sel:[1,0]
	v_pk_mul_f32 v[14:15], v[38:39], v[14:15] op_sel:[1,0]
	v_pk_mul_f32 v[16:17], v[38:39], v[16:17] op_sel:[1,0]
	v_lshl_add_u64 v[34:35], v[34:35], 0, v[166:167]
	v_pk_fma_f32 v[28:29], v[148:149], v[28:29], v[152:153]
	v_pk_fma_f32 v[26:27], v[146:147], v[26:27], v[150:151]
	v_pk_fma_f32 v[24:25], v[140:141], v[24:25], v[144:145]
	v_pk_fma_f32 v[22:23], v[138:139], v[22:23], v[142:143]
	v_pk_fma_f32 v[16:17], v[132:133], v[16:17], v[136:137]
	v_pk_fma_f32 v[14:15], v[130:131], v[14:15], v[134:135]
	global_store_dwordx4 v[34:35], v[30:33], off
	global_store_dwordx4 v[34:35], v[26:29], off offset:16
	global_store_dwordx4 v[34:35], v[22:25], off offset:512
	global_store_dwordx4 v[34:35], v[14:17], off offset:528
	ds_read_b64 v[22:23], v162 offset:9600
	v_add_u32_e32 v0, 0xb0, v0
	v_ashrrev_i32_e32 v1, 31, v0
	v_lshlrev_b64 v[0:1], 12, v[0:1]
	v_lshl_add_u64 v[0:1], s[52:53], 0, v[0:1]
	s_waitcnt lgkmcnt(0)
	v_sub_f32_e32 v15, v21, v22
	v_sub_f32_e32 v14, v20, v22
	v_sub_f32_e32 v17, v19, v22
	v_sub_f32_e32 v16, v18, v22
	v_pk_mul_f32 v[18:19], v[22:23], v[16:17] op_sel:[1,0]
	v_pk_mul_f32 v[14:15], v[22:23], v[14:15] op_sel:[1,0]
	v_sub_f32_e32 v11, v11, v22
	v_pk_fma_f32 v[16:17], v[156:157], v[14:15], v[160:161]
	v_pk_fma_f32 v[14:15], v[154:155], v[18:19], v[158:159]
	v_lshl_add_u64 v[18:19], v[0:1], 0, v[166:167]
	v_sub_f32_e32 v1, v13, v22
	v_sub_f32_e32 v0, v12, v22
	v_pk_mul_f32 v[0:1], v[22:23], v[0:1] op_sel:[1,0]
	v_sub_f32_e32 v10, v10, v22
	v_pk_fma_f32 v[12:13], v[148:149], v[0:1], v[152:153]
	v_sub_f32_e32 v1, v9, v22
	v_sub_f32_e32 v0, v8, v22
	v_pk_mul_f32 v[0:1], v[22:23], v[0:1] op_sel:[1,0]
	v_sub_f32_e32 v7, v7, v22
	v_sub_f32_e32 v6, v6, v22
	v_pk_fma_f32 v[8:9], v[140:141], v[0:1], v[144:145]
	v_sub_f32_e32 v1, v5, v22
	v_sub_f32_e32 v0, v4, v22
	v_sub_f32_e32 v3, v3, v22
	v_sub_f32_e32 v2, v2, v22
	v_pk_mul_f32 v[10:11], v[22:23], v[10:11] op_sel:[1,0]
	v_pk_mul_f32 v[6:7], v[22:23], v[6:7] op_sel:[1,0]
	v_pk_mul_f32 v[4:5], v[22:23], v[2:3] op_sel:[1,0]
	v_pk_mul_f32 v[0:1], v[22:23], v[0:1] op_sel:[1,0]
	v_pk_fma_f32 v[10:11], v[146:147], v[10:11], v[150:151]
	v_pk_fma_f32 v[6:7], v[138:139], v[6:7], v[142:143]
	v_pk_fma_f32 v[2:3], v[132:133], v[0:1], v[136:137]
	v_pk_fma_f32 v[0:1], v[130:131], v[4:5], v[134:135]

	.amdhsa_kernel _Z10fwd_kernel4Args
		.amdhsa_group_segment_fixed_size 0
		.amdhsa_private_segment_fixed_size 0
		.amdhsa_kernarg_size 512
		.amdhsa_user_sgpr_count 2
		.amdhsa_user_sgpr_dispatch_ptr 0
		.amdhsa_user_sgpr_queue_ptr 0
		.amdhsa_user_sgpr_kernarg_segment_ptr 1
		.amdhsa_user_sgpr_dispatch_id 0
		.amdhsa_user_sgpr_kernarg_preload_length 0
		.amdhsa_user_sgpr_kernarg_preload_offset 0
		.amdhsa_user_sgpr_private_segment_size 0
		.amdhsa_uses_dynamic_stack 0
		.amdhsa_enable_private_segment 0
		.amdhsa_system_sgpr_workgroup_id_x 1
		.amdhsa_system_sgpr_workgroup_id_y 0
		.amdhsa_system_sgpr_workgroup_id_z 0
		.amdhsa_system_sgpr_workgroup_info 0
		.amdhsa_system_vgpr_workitem_id 0
		.amdhsa_next_free_vgpr 243
		.amdhsa_next_free_sgpr 102
		.amdhsa_accum_offset 244
		.amdhsa_reserve_vcc 1
		.amdhsa_float_round_mode_32 0
		.amdhsa_float_round_mode_16_64 0
		.amdhsa_float_denorm_mode_32 3
		.amdhsa_float_denorm_mode_16_64 3
		.amdhsa_dx10_clamp 1
		.amdhsa_ieee_mode 1
		.amdhsa_fp16_overflow 0
		.amdhsa_tg_split 0
		.amdhsa_exception_fp_ieee_invalid_op 0
		.amdhsa_exception_fp_denorm_src 0
		.amdhsa_exception_fp_ieee_div_zero 0
		.amdhsa_exception_fp_ieee_overflow 0
		.amdhsa_exception_fp_ieee_underflow 0
		.amdhsa_exception_fp_ieee_inexact 0
		.amdhsa_exception_int_div_zero 0
	.end_amdhsa_kernel

amdhsa.kernels:
  - .agpr_count:     0
    .args:
      - .offset:         0
        .size:           256
        .value_kind:     by_value
      - .offset:         256
        .size:           4
        .value_kind:     hidden_block_count_x
      - .offset:         260
        .size:           4
        .value_kind:     hidden_block_count_y
      - .offset:         264
        .size:           4
        .value_kind:     hidden_block_count_z
      - .offset:         268
        .size:           2
        .value_kind:     hidden_group_size_x
      - .offset:         270
        .size:           2
        .value_kind:     hidden_group_size_y
      - .offset:         272
        .size:           2
        .value_kind:     hidden_group_size_z
      - .offset:         274
        .size:           2
        .value_kind:     hidden_remainder_x
      - .offset:         276
        .size:           2
        .value_kind:     hidden_remainder_y
      - .offset:         278
        .size:           2
        .value_kind:     hidden_remainder_z
      - .offset:         296
        .size:           8
        .value_kind:     hidden_global_offset_x
      - .offset:         304
        .size:           8
        .value_kind:     hidden_global_offset_y
      - .offset:         312
        .size:           8
        .value_kind:     hidden_global_offset_z
      - .offset:         320
        .size:           2
        .value_kind:     hidden_grid_dims
      - .offset:         376
        .size:           4
        .value_kind:     hidden_dynamic_lds_size
    .group_segment_fixed_size: 0
    .kernarg_segment_align: 8
    .kernarg_segment_size: 512
    .language:       OpenCL C
    .language_version:
      - 2
      - 0
    .max_flat_workgroup_size: 512
    .name:           _Z10fwd_kernel4Args
    .private_segment_fixed_size: 0
    .sgpr_count:     108
    .sgpr_spill_count: 42
    .symbol:         _Z10fwd_kernel4Args.kd
    .uniform_work_group_size: 1
    .uses_dynamic_stack: false
    .vgpr_count:     243
    .vgpr_spill_count: 0
    .wavefront_size: 64
